# GEMM K-loops: 58 LDS-DMA loads switched to SGPR-base + 32-bit VGPR offset form, dropping their 64-bit VALU address adds (on top of look-back pipeline)
# baseline (speedup 1.0000x reference)
.LBB0_256:
	ds_read_b128 v[32:35], v225
	ds_read_b128 v[36:39], v225 offset:1024
	ds_read_b128 v[40:43], v225 offset:2048
	ds_read_b128 v[44:47], v225 offset:3072
	ds_read_b128 v[144:147], v228
	ds_read_b128 v[148:151], v228 offset:1024
	ds_read_b128 v[152:155], v228 offset:2048
	ds_read_b128 v[156:159], v228 offset:3072
	s_add_u32 s12, s10, 0xfffc0080
	s_addc_u32 s13, s11, -1
	s_cmp_eq_u32 s59, 12
	s_cselect_b32 s37, s1, s13
	s_cselect_b32 s36, s3, s12
	s_cselect_b32 s13, s27, s58
	s_cselect_b32 s12, s29, s33
	s_add_i32 m0, s43, 0xc000
	ds_read_b128 v[160:163], v229
	ds_read_b128 v[164:167], v229 offset:1024
	ds_read_b128 v[168:171], v229 offset:2048
	ds_read_b128 v[172:175], v229 offset:3072
	ds_read_b128 v[176:179], v229 offset:4096
	ds_read_b128 v[180:183], v229 offset:5120
	ds_read_b128 v[184:187], v229 offset:6144
	ds_read_b128 v[188:191], v229 offset:7168
	global_load_lds_dwordx4 v206, s[10:11]
	s_add_i32 m0, s43, 0xe000
	s_nop 0
	global_load_lds_dwordx4 v208, s[10:11]
	s_waitcnt vmcnt(8)
	s_waitcnt lgkmcnt(0)
	s_barrier
	s_setprio 1
	s_waitcnt lgkmcnt(0)
	v_mfma_f32_16x16x32_bf16 v[140:143], v[32:35], v[160:163], v[140:143]
	v_mfma_f32_16x16x32_bf16 v[136:139], v[40:43], v[160:163], v[136:139]
	v_mfma_f32_16x16x32_bf16 v[124:127], v[32:35], v[168:171], v[124:127]
	v_mfma_f32_16x16x32_bf16 v[120:123], v[40:43], v[168:171], v[120:123]
	v_mfma_f32_16x16x32_bf16 v[108:111], v[32:35], v[176:179], v[108:111]
	v_mfma_f32_16x16x32_bf16 v[104:107], v[40:43], v[176:179], v[104:107]
	v_mfma_f32_16x16x32_bf16 v[92:95], v[32:35], v[184:187], v[92:95]
	v_mfma_f32_16x16x32_bf16 v[88:91], v[40:43], v[184:187], v[88:91]
	v_mfma_f32_16x16x32_bf16 v[140:143], v[36:39], v[164:167], v[140:143]
	v_mfma_f32_16x16x32_bf16 v[136:139], v[44:47], v[164:167], v[136:139]
	v_mfma_f32_16x16x32_bf16 v[124:127], v[36:39], v[172:175], v[124:127]
	v_mfma_f32_16x16x32_bf16 v[120:123], v[44:47], v[172:175], v[120:123]
	v_mfma_f32_16x16x32_bf16 v[108:111], v[36:39], v[180:183], v[108:111]
	v_mfma_f32_16x16x32_bf16 v[104:107], v[44:47], v[180:183], v[104:107]
	v_mfma_f32_16x16x32_bf16 v[92:95], v[36:39], v[188:191], v[92:95]
	v_mfma_f32_16x16x32_bf16 v[88:91], v[44:47], v[188:191], v[88:91]
	s_setprio 0
	s_setprio 1
	v_mfma_f32_16x16x32_bf16 v[132:135], v[144:147], v[160:163], v[132:135]
	v_mfma_f32_16x16x32_bf16 v[128:131], v[152:155], v[160:163], v[128:131]
	v_mfma_f32_16x16x32_bf16 v[116:119], v[144:147], v[168:171], v[116:119]
	v_mfma_f32_16x16x32_bf16 v[112:115], v[152:155], v[168:171], v[112:115]
	v_mfma_f32_16x16x32_bf16 v[100:103], v[144:147], v[176:179], v[100:103]
	v_mfma_f32_16x16x32_bf16 v[96:99], v[152:155], v[176:179], v[96:99]
	v_mfma_f32_16x16x32_bf16 v[84:87], v[144:147], v[184:187], v[84:87]
	v_mfma_f32_16x16x32_bf16 v[80:83], v[152:155], v[184:187], v[80:83]
	v_mfma_f32_16x16x32_bf16 v[132:135], v[148:151], v[164:167], v[132:135]
	v_mfma_f32_16x16x32_bf16 v[128:131], v[156:159], v[164:167], v[128:131]
	v_mfma_f32_16x16x32_bf16 v[116:119], v[148:151], v[172:175], v[116:119]
	v_mfma_f32_16x16x32_bf16 v[112:115], v[156:159], v[172:175], v[112:115]
	v_mfma_f32_16x16x32_bf16 v[100:103], v[148:151], v[180:183], v[100:103]
	v_mfma_f32_16x16x32_bf16 v[96:99], v[156:159], v[180:183], v[96:99]
	v_mfma_f32_16x16x32_bf16 v[84:87], v[148:151], v[188:191], v[84:87]
	v_mfma_f32_16x16x32_bf16 v[80:83], v[156:159], v[188:191], v[80:83]
	s_setprio 0
	s_barrier
	s_add_i32 s60, s54, s42
	v_lshl_add_u64 v[216:217], s[12:13], 0, v[194:195]
	s_mov_b32 m0, s60
	ds_read_b128 v[160:163], v229 offset:16384
	ds_read_b128 v[164:167], v229 offset:17408
	ds_read_b128 v[168:171], v229 offset:18432
	ds_read_b128 v[172:175], v229 offset:19456
	ds_read_b128 v[176:179], v229 offset:20480
	ds_read_b128 v[180:183], v229 offset:21504
	ds_read_b128 v[184:187], v229 offset:22528
	ds_read_b128 v[188:191], v229 offset:23552
	global_load_lds_dwordx4 v[216:217], off
	s_add_i32 m0, s60, 0x2000
	s_add_u32 s60, s12, 0x40000
	v_lshl_add_u64 v[218:219], s[12:13], 0, v[198:199]
	s_addc_u32 s61, s13, 0
	s_add_i32 s62, s55, s42
	global_load_lds_dwordx4 v[218:219], off
	s_mov_b32 m0, s62
	v_lshl_add_u64 v[222:223], s[36:37], 0, v[196:197]
	global_load_lds_dwordx4 v194, s[60:61]
	s_add_i32 m0, s62, 0x2000
	s_nop 0
	global_load_lds_dwordx4 v198, s[60:61]
	v_lshl_add_u64 v[220:221], s[36:37], 0, v[192:193]
	s_mov_b32 m0, s43
	s_nop 0
	global_load_lds_dwordx4 v[220:221], off
	s_mov_b32 m0, s44
	s_nop 0
	global_load_lds_dwordx4 v[222:223], off
	s_waitcnt vmcnt(8)
	s_waitcnt lgkmcnt(0)
	s_barrier
	s_setprio 1
	s_waitcnt lgkmcnt(0)
	v_mfma_f32_16x16x32_bf16 v[76:79], v[32:35], v[160:163], v[76:79]
	v_mfma_f32_16x16x32_bf16 v[72:75], v[40:43], v[160:163], v[72:75]
	v_mfma_f32_16x16x32_bf16 v[60:63], v[32:35], v[168:171], v[60:63]
	v_mfma_f32_16x16x32_bf16 v[56:59], v[40:43], v[168:171], v[56:59]
	v_mfma_f32_16x16x32_bf16 v[28:31], v[32:35], v[176:179], v[28:31]
	v_mfma_f32_16x16x32_bf16 v[24:27], v[40:43], v[176:179], v[24:27]
	v_mfma_f32_16x16x32_bf16 v[12:15], v[32:35], v[184:187], v[12:15]
	v_mfma_f32_16x16x32_bf16 v[8:11], v[40:43], v[184:187], v[8:11]
	v_mfma_f32_16x16x32_bf16 v[76:79], v[36:39], v[164:167], v[76:79]
	v_mfma_f32_16x16x32_bf16 v[72:75], v[44:47], v[164:167], v[72:75]
	v_mfma_f32_16x16x32_bf16 v[60:63], v[36:39], v[172:175], v[60:63]
	v_mfma_f32_16x16x32_bf16 v[56:59], v[44:47], v[172:175], v[56:59]
	v_mfma_f32_16x16x32_bf16 v[28:31], v[36:39], v[180:183], v[28:31]
	v_mfma_f32_16x16x32_bf16 v[24:27], v[44:47], v[180:183], v[24:27]
	v_mfma_f32_16x16x32_bf16 v[12:15], v[36:39], v[188:191], v[12:15]
	v_mfma_f32_16x16x32_bf16 v[8:11], v[44:47], v[188:191], v[8:11]
	s_setprio 0
	s_setprio 1
	v_mfma_f32_16x16x32_bf16 v[20:23], v[144:147], v[176:179], v[20:23]
	v_mfma_f32_16x16x32_bf16 v[16:19], v[152:155], v[176:179], v[16:19]
	v_mfma_f32_16x16x32_bf16 v[4:7], v[144:147], v[184:187], v[4:7]
	v_mfma_f32_16x16x32_bf16 v[0:3], v[152:155], v[184:187], v[0:3]
	v_mfma_f32_16x16x32_bf16 v[32:35], v[144:147], v[160:163], v[68:71]
	v_mfma_f32_16x16x32_bf16 v[36:39], v[152:155], v[160:163], v[64:67]
	v_mfma_f32_16x16x32_bf16 v[40:43], v[144:147], v[168:171], v[52:55]
	v_mfma_f32_16x16x32_bf16 v[44:47], v[152:155], v[168:171], v[48:51]
	v_mfma_f32_16x16x32_bf16 v[20:23], v[148:151], v[180:183], v[20:23]
	v_mfma_f32_16x16x32_bf16 v[16:19], v[156:159], v[180:183], v[16:19]
	v_mfma_f32_16x16x32_bf16 v[4:7], v[148:151], v[188:191], v[4:7]
	v_mfma_f32_16x16x32_bf16 v[0:3], v[156:159], v[188:191], v[0:3]
	v_mfma_f32_16x16x32_bf16 v[32:35], v[148:151], v[164:167], v[32:35]
	v_mfma_f32_16x16x32_bf16 v[36:39], v[156:159], v[164:167], v[36:39]
	v_mfma_f32_16x16x32_bf16 v[40:43], v[148:151], v[172:175], v[40:43]
	v_mfma_f32_16x16x32_bf16 v[44:47], v[156:159], v[172:175], v[44:47]
	s_setprio 0
	s_barrier
	s_add_i32 s60, 0, 0x18000
	s_add_i32 s61, 0, 0x1c000
	v_add_u32_e32 v68, s60, v224
	v_add_u32_e32 v156, s61, v224
	ds_read_b128 v[48:51], v68
	ds_read_b128 v[52:55], v68 offset:1024
	ds_read_b128 v[64:67], v68 offset:2048
	ds_read_b128 v[68:71], v68 offset:3072
	ds_read_b128 v[144:147], v156
	ds_read_b128 v[148:151], v156 offset:1024
	ds_read_b128 v[152:155], v156 offset:2048
	ds_read_b128 v[156:159], v156 offset:3072
	s_add_u32 s36, s36, 0x40000
	s_addc_u32 s37, s37, 0
	s_mov_b32 m0, s45
	ds_read_b128 v[160:163], v229 offset:32768
	ds_read_b128 v[164:167], v229 offset:33792
	ds_read_b128 v[168:171], v229 offset:34816
	ds_read_b128 v[172:175], v229 offset:35840
	ds_read_b128 v[176:179], v229 offset:36864
	ds_read_b128 v[180:183], v229 offset:37888
	ds_read_b128 v[184:187], v229 offset:38912
	ds_read_b128 v[188:191], v229 offset:39936
	global_load_lds_dwordx4 v192, s[36:37]
	s_mov_b32 m0, s46
	s_nop 0
	global_load_lds_dwordx4 v196, s[36:37]
	s_waitcnt vmcnt(8)
	s_waitcnt lgkmcnt(0)
	s_barrier
	s_setprio 1
	s_waitcnt lgkmcnt(0)
	v_mfma_f32_16x16x32_bf16 v[140:143], v[48:51], v[160:163], v[140:143]
	v_mfma_f32_16x16x32_bf16 v[136:139], v[64:67], v[160:163], v[136:139]
	v_mfma_f32_16x16x32_bf16 v[124:127], v[48:51], v[168:171], v[124:127]
	v_mfma_f32_16x16x32_bf16 v[120:123], v[64:67], v[168:171], v[120:123]
	v_mfma_f32_16x16x32_bf16 v[108:111], v[48:51], v[176:179], v[108:111]
	v_mfma_f32_16x16x32_bf16 v[104:107], v[64:67], v[176:179], v[104:107]
	v_mfma_f32_16x16x32_bf16 v[92:95], v[48:51], v[184:187], v[92:95]
	v_mfma_f32_16x16x32_bf16 v[88:91], v[64:67], v[184:187], v[88:91]
	v_mfma_f32_16x16x32_bf16 v[140:143], v[52:55], v[164:167], v[140:143]
	v_mfma_f32_16x16x32_bf16 v[136:139], v[68:71], v[164:167], v[136:139]
	v_mfma_f32_16x16x32_bf16 v[124:127], v[52:55], v[172:175], v[124:127]
	v_mfma_f32_16x16x32_bf16 v[120:123], v[68:71], v[172:175], v[120:123]
	v_mfma_f32_16x16x32_bf16 v[108:111], v[52:55], v[180:183], v[108:111]
	v_mfma_f32_16x16x32_bf16 v[104:107], v[68:71], v[180:183], v[104:107]
	v_mfma_f32_16x16x32_bf16 v[92:95], v[52:55], v[188:191], v[92:95]
	v_mfma_f32_16x16x32_bf16 v[88:91], v[68:71], v[188:191], v[88:91]
	s_setprio 0
	s_setprio 1
	v_mfma_f32_16x16x32_bf16 v[132:135], v[144:147], v[160:163], v[132:135]
	v_mfma_f32_16x16x32_bf16 v[128:131], v[152:155], v[160:163], v[128:131]
	v_mfma_f32_16x16x32_bf16 v[116:119], v[144:147], v[168:171], v[116:119]
	v_mfma_f32_16x16x32_bf16 v[112:115], v[152:155], v[168:171], v[112:115]
	v_mfma_f32_16x16x32_bf16 v[100:103], v[144:147], v[176:179], v[100:103]
	v_mfma_f32_16x16x32_bf16 v[96:99], v[152:155], v[176:179], v[96:99]
	v_mfma_f32_16x16x32_bf16 v[84:87], v[144:147], v[184:187], v[84:87]
	v_mfma_f32_16x16x32_bf16 v[80:83], v[152:155], v[184:187], v[80:83]
	v_mfma_f32_16x16x32_bf16 v[132:135], v[148:151], v[164:167], v[132:135]
	v_mfma_f32_16x16x32_bf16 v[128:131], v[156:159], v[164:167], v[128:131]
	v_mfma_f32_16x16x32_bf16 v[116:119], v[148:151], v[172:175], v[116:119]
	v_mfma_f32_16x16x32_bf16 v[112:115], v[156:159], v[172:175], v[112:115]
	v_mfma_f32_16x16x32_bf16 v[100:103], v[148:151], v[180:183], v[100:103]
	v_mfma_f32_16x16x32_bf16 v[96:99], v[156:159], v[180:183], v[96:99]
	v_mfma_f32_16x16x32_bf16 v[84:87], v[148:151], v[188:191], v[84:87]
	v_mfma_f32_16x16x32_bf16 v[80:83], v[156:159], v[188:191], v[80:83]
	s_setprio 0
	s_barrier
	s_add_i32 s36, s60, s42
	v_lshl_add_u64 v[216:217], v[216:217], 0, s[22:23]
	s_mov_b32 m0, s36
	ds_read_b128 v[160:163], v229 offset:49152
	ds_read_b128 v[164:167], v229 offset:50176
	ds_read_b128 v[168:171], v229 offset:51200
	ds_read_b128 v[172:175], v229 offset:52224
	ds_read_b128 v[176:179], v229 offset:53248
	ds_read_b128 v[180:183], v229 offset:54272
	ds_read_b128 v[184:187], v229 offset:55296
	ds_read_b128 v[188:191], v229 offset:56320
	global_load_lds_dwordx4 v[216:217], off
	s_add_i32 m0, s36, 0x2000
	s_add_u32 s12, s12, 0x40080
	v_lshl_add_u64 v[216:217], v[218:219], 0, s[22:23]
	s_addc_u32 s13, s13, 0
	s_add_i32 s36, s61, s42
	global_load_lds_dwordx4 v[216:217], off
	s_mov_b32 m0, s36
	s_nop 0
	global_load_lds_dwordx4 v194, s[12:13]
	s_add_i32 m0, s36, 0x2000
	s_nop 0
	global_load_lds_dwordx4 v198, s[12:13]
	v_lshl_add_u64 v[216:217], v[220:221], 0, s[22:23]
	s_mov_b32 m0, s49
	s_nop 0
	global_load_lds_dwordx4 v[216:217], off
	v_lshl_add_u64 v[216:217], v[222:223], 0, s[22:23]
	s_mov_b32 m0, s50
	s_nop 0
	global_load_lds_dwordx4 v[216:217], off
	s_waitcnt vmcnt(8)
	s_waitcnt lgkmcnt(0)
	s_barrier
	s_setprio 1
	s_waitcnt lgkmcnt(0)
	v_mfma_f32_16x16x32_bf16 v[76:79], v[48:51], v[160:163], v[76:79]
	v_mfma_f32_16x16x32_bf16 v[72:75], v[64:67], v[160:163], v[72:75]
	v_mfma_f32_16x16x32_bf16 v[60:63], v[48:51], v[168:171], v[60:63]
	v_mfma_f32_16x16x32_bf16 v[56:59], v[64:67], v[168:171], v[56:59]
	v_mfma_f32_16x16x32_bf16 v[28:31], v[48:51], v[176:179], v[28:31]
	v_mfma_f32_16x16x32_bf16 v[24:27], v[64:67], v[176:179], v[24:27]
	v_mfma_f32_16x16x32_bf16 v[12:15], v[48:51], v[184:187], v[12:15]
	v_mfma_f32_16x16x32_bf16 v[8:11], v[64:67], v[184:187], v[8:11]
	v_mfma_f32_16x16x32_bf16 v[76:79], v[52:55], v[164:167], v[76:79]
	v_mfma_f32_16x16x32_bf16 v[72:75], v[68:71], v[164:167], v[72:75]
	v_mfma_f32_16x16x32_bf16 v[60:63], v[52:55], v[172:175], v[60:63]
	v_mfma_f32_16x16x32_bf16 v[56:59], v[68:71], v[172:175], v[56:59]
	v_mfma_f32_16x16x32_bf16 v[28:31], v[52:55], v[180:183], v[28:31]
	v_mfma_f32_16x16x32_bf16 v[24:27], v[68:71], v[180:183], v[24:27]
	v_mfma_f32_16x16x32_bf16 v[12:15], v[52:55], v[188:191], v[12:15]
	v_mfma_f32_16x16x32_bf16 v[8:11], v[68:71], v[188:191], v[8:11]
	s_setprio 0
	s_setprio 1
	v_mfma_f32_16x16x32_bf16 v[32:35], v[144:147], v[160:163], v[32:35]
	v_mfma_f32_16x16x32_bf16 v[68:71], v[148:151], v[164:167], v[32:35]
	v_mfma_f32_16x16x32_bf16 v[32:35], v[152:155], v[160:163], v[36:39]
	v_mfma_f32_16x16x32_bf16 v[64:67], v[156:159], v[164:167], v[32:35]
	v_mfma_f32_16x16x32_bf16 v[32:35], v[144:147], v[168:171], v[40:43]
	v_mfma_f32_16x16x32_bf16 v[52:55], v[148:151], v[172:175], v[32:35]
	v_mfma_f32_16x16x32_bf16 v[32:35], v[152:155], v[168:171], v[44:47]
	v_mfma_f32_16x16x32_bf16 v[20:23], v[144:147], v[176:179], v[20:23]
	v_mfma_f32_16x16x32_bf16 v[16:19], v[152:155], v[176:179], v[16:19]
	v_mfma_f32_16x16x32_bf16 v[4:7], v[144:147], v[184:187], v[4:7]
	v_mfma_f32_16x16x32_bf16 v[0:3], v[152:155], v[184:187], v[0:3]
	v_mfma_f32_16x16x32_bf16 v[48:51], v[156:159], v[172:175], v[32:35]
	v_mfma_f32_16x16x32_bf16 v[20:23], v[148:151], v[180:183], v[20:23]
	v_mfma_f32_16x16x32_bf16 v[16:19], v[156:159], v[180:183], v[16:19]
	v_mfma_f32_16x16x32_bf16 v[4:7], v[148:151], v[188:191], v[4:7]
	v_mfma_f32_16x16x32_bf16 v[0:3], v[156:159], v[188:191], v[0:3]
	s_setprio 0
	s_barrier
	s_add_i32 s59, s59, 2
	s_add_u32 s10, s10, 0x100
	s_addc_u32 s11, s11, 0
	s_add_u32 s33, s33, 0x100
	s_addc_u32 s58, s58, 0
	s_cmp_gt_u32 s59, 13
	s_cbranch_scc0 .LBB0_256
	s_and_b64 vcc, exec, s[24:25]
	s_cbranch_vccz .LBB0_259
	s_barrier

.LBB0_611:
	ds_read_b128 v[140:143], v134
	ds_read_b128 v[144:147], v134 offset:1024
	ds_read_b128 v[148:151], v134 offset:2048
	ds_read_b128 v[164:167], v134 offset:3072
	ds_read_b128 v[168:171], v135
	ds_read_b128 v[172:175], v135 offset:1024
	ds_read_b128 v[176:179], v135 offset:2048
	ds_read_b128 v[206:209], v135 offset:3072
	s_add_u32 s10, s8, 0xfffc0080
	s_addc_u32 s11, s9, -1
	s_cmp_lg_u32 s22, 12
	s_cselect_b32 s10, s10, 0
	s_cselect_b32 s11, s11, 0
	s_add_u32 s12, s4, s10
	s_addc_u32 s13, s5, s11
	s_add_u32 s10, s2, s10
	s_addc_u32 s11, s3, s11
	s_mov_b32 m0, s23
	v_lshl_add_u64 v[180:181], v[128:129], 0, s[8:9]
	ds_read_b128 v[210:213], v136
	ds_read_b128 v[214:217], v136 offset:1024
	ds_read_b128 v[218:221], v136 offset:2048
	ds_read_b128 v[222:225], v136 offset:3072
	ds_read_b128 v[232:235], v136 offset:4096
	ds_read_b128 v[236:239], v136 offset:5120
	ds_read_b128 v[240:243], v136 offset:6144
	ds_read_b128 v[244:247], v136 offset:7168
	global_load_lds_dwordx4 v[180:181], off
	v_lshl_add_u64 v[180:181], v[130:131], 0, s[8:9]
	s_mov_b32 m0, s29
	s_nop 0
	global_load_lds_dwordx4 v[180:181], off
	s_waitcnt vmcnt(8)
	s_waitcnt lgkmcnt(0)
	s_barrier
	s_setprio 1
	s_waitcnt lgkmcnt(0)
	v_mfma_f32_16x16x32_bf16 v[124:127], v[140:143], v[210:213], v[124:127]
	v_mfma_f32_16x16x32_bf16 v[120:123], v[148:151], v[210:213], v[120:123]
	v_mfma_f32_16x16x32_bf16 v[108:111], v[140:143], v[218:221], v[108:111]
	v_mfma_f32_16x16x32_bf16 v[104:107], v[148:151], v[218:221], v[104:107]
	v_mfma_f32_16x16x32_bf16 v[92:95], v[140:143], v[232:235], v[92:95]
	v_mfma_f32_16x16x32_bf16 v[88:91], v[148:151], v[232:235], v[88:91]
	v_mfma_f32_16x16x32_bf16 v[76:79], v[140:143], v[240:243], v[76:79]
	v_mfma_f32_16x16x32_bf16 v[72:75], v[148:151], v[240:243], v[72:75]
	v_mfma_f32_16x16x32_bf16 v[124:127], v[144:147], v[214:217], v[124:127]
	v_mfma_f32_16x16x32_bf16 v[120:123], v[164:167], v[214:217], v[120:123]
	v_mfma_f32_16x16x32_bf16 v[108:111], v[144:147], v[222:225], v[108:111]
	v_mfma_f32_16x16x32_bf16 v[104:107], v[164:167], v[222:225], v[104:107]
	v_mfma_f32_16x16x32_bf16 v[92:95], v[144:147], v[236:239], v[92:95]
	v_mfma_f32_16x16x32_bf16 v[88:91], v[164:167], v[236:239], v[88:91]
	v_mfma_f32_16x16x32_bf16 v[76:79], v[144:147], v[244:247], v[76:79]
	v_mfma_f32_16x16x32_bf16 v[72:75], v[164:167], v[244:247], v[72:75]
	s_setprio 0
	s_setprio 1
	v_mfma_f32_16x16x32_bf16 v[116:119], v[168:171], v[210:213], v[116:119]
	v_mfma_f32_16x16x32_bf16 v[112:115], v[176:179], v[210:213], v[112:115]
	v_mfma_f32_16x16x32_bf16 v[100:103], v[168:171], v[218:221], v[100:103]
	v_mfma_f32_16x16x32_bf16 v[96:99], v[176:179], v[218:221], v[96:99]
	v_mfma_f32_16x16x32_bf16 v[84:87], v[168:171], v[232:235], v[84:87]
	v_mfma_f32_16x16x32_bf16 v[80:83], v[176:179], v[232:235], v[80:83]
	v_mfma_f32_16x16x32_bf16 v[68:71], v[168:171], v[240:243], v[68:71]
	v_mfma_f32_16x16x32_bf16 v[64:67], v[176:179], v[240:243], v[64:67]
	v_mfma_f32_16x16x32_bf16 v[116:119], v[172:175], v[214:217], v[116:119]
	v_mfma_f32_16x16x32_bf16 v[112:115], v[206:209], v[214:217], v[112:115]
	v_mfma_f32_16x16x32_bf16 v[100:103], v[172:175], v[222:225], v[100:103]
	v_mfma_f32_16x16x32_bf16 v[96:99], v[206:209], v[222:225], v[96:99]
	v_mfma_f32_16x16x32_bf16 v[84:87], v[172:175], v[236:239], v[84:87]
	v_mfma_f32_16x16x32_bf16 v[80:83], v[206:209], v[236:239], v[80:83]
	v_mfma_f32_16x16x32_bf16 v[68:71], v[172:175], v[244:247], v[68:71]
	v_mfma_f32_16x16x32_bf16 v[64:67], v[206:209], v[244:247], v[64:67]
	s_setprio 0
	s_barrier
	s_mov_b32 m0, s30
	v_lshl_add_u64 v[180:181], s[10:11], 0, v[156:157]
	s_add_u32 s50, s10, 0x40000
	ds_read_b128 v[210:213], v136 offset:16384
	ds_read_b128 v[214:217], v136 offset:17408
	ds_read_b128 v[218:221], v136 offset:18432
	ds_read_b128 v[222:225], v136 offset:19456
	ds_read_b128 v[232:235], v136 offset:20480
	ds_read_b128 v[236:239], v136 offset:21504
	ds_read_b128 v[240:243], v136 offset:22528
	ds_read_b128 v[244:247], v136 offset:23552
	global_load_lds_dwordx4 v[180:181], off
	v_lshl_add_u64 v[202:203], s[10:11], 0, v[152:153]
	s_mov_b32 m0, s31
	s_addc_u32 s51, s11, 0
	global_load_lds_dwordx4 v[202:203], off
	s_mov_b32 m0, s33
	v_lshl_add_u64 v[250:251], s[12:13], 0, v[154:155]
	global_load_lds_dwordx4 v156, s[50:51]
	s_mov_b32 m0, s34
	s_nop 0
	global_load_lds_dwordx4 v152, s[50:51]
	v_lshl_add_u64 v[248:249], s[12:13], 0, v[158:159]
	s_mov_b32 m0, s16
	s_nop 0
	global_load_lds_dwordx4 v[248:249], off
	s_mov_b32 m0, s17
	s_nop 0
	global_load_lds_dwordx4 v[250:251], off
	s_waitcnt vmcnt(8)
	s_waitcnt lgkmcnt(0)
	s_barrier
	s_setprio 1
	s_waitcnt lgkmcnt(0)
	v_mfma_f32_16x16x32_bf16 v[60:63], v[140:143], v[210:213], v[60:63]
	v_mfma_f32_16x16x32_bf16 v[56:59], v[148:151], v[210:213], v[56:59]
	v_mfma_f32_16x16x32_bf16 v[44:47], v[140:143], v[218:221], v[44:47]
	v_mfma_f32_16x16x32_bf16 v[40:43], v[148:151], v[218:221], v[40:43]
	v_mfma_f32_16x16x32_bf16 v[28:31], v[140:143], v[232:235], v[28:31]
	v_mfma_f32_16x16x32_bf16 v[24:27], v[148:151], v[232:235], v[24:27]
	v_mfma_f32_16x16x32_bf16 v[12:15], v[140:143], v[240:243], v[12:15]
	v_mfma_f32_16x16x32_bf16 v[8:11], v[148:151], v[240:243], v[8:11]
	v_mfma_f32_16x16x32_bf16 v[60:63], v[144:147], v[214:217], v[60:63]
	v_mfma_f32_16x16x32_bf16 v[56:59], v[164:167], v[214:217], v[56:59]
	v_mfma_f32_16x16x32_bf16 v[44:47], v[144:147], v[222:225], v[44:47]
	v_mfma_f32_16x16x32_bf16 v[40:43], v[164:167], v[222:225], v[40:43]
	v_mfma_f32_16x16x32_bf16 v[28:31], v[144:147], v[236:239], v[28:31]
	v_mfma_f32_16x16x32_bf16 v[24:27], v[164:167], v[236:239], v[24:27]
	v_mfma_f32_16x16x32_bf16 v[12:15], v[144:147], v[244:247], v[12:15]
	v_mfma_f32_16x16x32_bf16 v[8:11], v[164:167], v[244:247], v[8:11]
	s_setprio 0
	s_setprio 1
	v_mfma_f32_16x16x32_bf16 v[52:55], v[168:171], v[210:213], v[52:55]
	v_mfma_f32_16x16x32_bf16 v[48:51], v[176:179], v[210:213], v[48:51]
	v_mfma_f32_16x16x32_bf16 v[36:39], v[168:171], v[218:221], v[36:39]
	v_mfma_f32_16x16x32_bf16 v[32:35], v[176:179], v[218:221], v[32:35]
	v_mfma_f32_16x16x32_bf16 v[20:23], v[168:171], v[232:235], v[20:23]
	v_mfma_f32_16x16x32_bf16 v[16:19], v[176:179], v[232:235], v[16:19]
	v_mfma_f32_16x16x32_bf16 v[4:7], v[168:171], v[240:243], v[4:7]
	v_mfma_f32_16x16x32_bf16 v[0:3], v[176:179], v[240:243], v[0:3]
	v_mfma_f32_16x16x32_bf16 v[52:55], v[172:175], v[214:217], v[52:55]
	v_mfma_f32_16x16x32_bf16 v[48:51], v[206:209], v[214:217], v[48:51]
	v_mfma_f32_16x16x32_bf16 v[36:39], v[172:175], v[222:225], v[36:39]
	v_mfma_f32_16x16x32_bf16 v[32:35], v[206:209], v[222:225], v[32:35]
	v_mfma_f32_16x16x32_bf16 v[20:23], v[172:175], v[236:239], v[20:23]
	v_mfma_f32_16x16x32_bf16 v[16:19], v[206:209], v[236:239], v[16:19]
	v_mfma_f32_16x16x32_bf16 v[4:7], v[172:175], v[244:247], v[4:7]
	v_mfma_f32_16x16x32_bf16 v[0:3], v[206:209], v[244:247], v[0:3]
	s_setprio 0
	s_barrier
	ds_read_b128 v[140:143], v137
	ds_read_b128 v[144:147], v137 offset:1024
	ds_read_b128 v[148:151], v137 offset:2048
	ds_read_b128 v[164:167], v137 offset:3072
	ds_read_b128 v[168:171], v138
	ds_read_b128 v[172:175], v138 offset:1024
	ds_read_b128 v[176:179], v138 offset:2048
	ds_read_b128 v[206:209], v138 offset:3072
	s_add_u32 s12, s12, 0x40000
	s_addc_u32 s13, s13, 0
	s_mov_b32 m0, s18
	ds_read_b128 v[210:213], v136 offset:32768
	ds_read_b128 v[214:217], v136 offset:33792
	ds_read_b128 v[218:221], v136 offset:34816
	ds_read_b128 v[222:225], v136 offset:35840
	ds_read_b128 v[232:235], v136 offset:36864
	ds_read_b128 v[236:239], v136 offset:37888
	ds_read_b128 v[240:243], v136 offset:38912
	ds_read_b128 v[244:247], v136 offset:39936
	global_load_lds_dwordx4 v158, s[12:13]
	s_mov_b32 m0, s19
	s_nop 0
	global_load_lds_dwordx4 v154, s[12:13]
	s_waitcnt vmcnt(8)
	s_waitcnt lgkmcnt(0)
	s_barrier
	s_setprio 1
	s_waitcnt lgkmcnt(0)
	v_mfma_f32_16x16x32_bf16 v[124:127], v[140:143], v[210:213], v[124:127]
	v_mfma_f32_16x16x32_bf16 v[120:123], v[148:151], v[210:213], v[120:123]
	v_mfma_f32_16x16x32_bf16 v[108:111], v[140:143], v[218:221], v[108:111]
	v_mfma_f32_16x16x32_bf16 v[104:107], v[148:151], v[218:221], v[104:107]
	v_mfma_f32_16x16x32_bf16 v[92:95], v[140:143], v[232:235], v[92:95]
	v_mfma_f32_16x16x32_bf16 v[88:91], v[148:151], v[232:235], v[88:91]
	v_mfma_f32_16x16x32_bf16 v[76:79], v[140:143], v[240:243], v[76:79]
	v_mfma_f32_16x16x32_bf16 v[72:75], v[148:151], v[240:243], v[72:75]
	v_mfma_f32_16x16x32_bf16 v[124:127], v[144:147], v[214:217], v[124:127]
	v_mfma_f32_16x16x32_bf16 v[120:123], v[164:167], v[214:217], v[120:123]
	v_mfma_f32_16x16x32_bf16 v[108:111], v[144:147], v[222:225], v[108:111]
	v_mfma_f32_16x16x32_bf16 v[104:107], v[164:167], v[222:225], v[104:107]
	v_mfma_f32_16x16x32_bf16 v[92:95], v[144:147], v[236:239], v[92:95]
	v_mfma_f32_16x16x32_bf16 v[88:91], v[164:167], v[236:239], v[88:91]
	v_mfma_f32_16x16x32_bf16 v[76:79], v[144:147], v[244:247], v[76:79]
	v_mfma_f32_16x16x32_bf16 v[72:75], v[164:167], v[244:247], v[72:75]
	s_setprio 0
	s_setprio 1
	v_mfma_f32_16x16x32_bf16 v[116:119], v[168:171], v[210:213], v[116:119]
	v_mfma_f32_16x16x32_bf16 v[112:115], v[176:179], v[210:213], v[112:115]
	v_mfma_f32_16x16x32_bf16 v[100:103], v[168:171], v[218:221], v[100:103]
	v_mfma_f32_16x16x32_bf16 v[96:99], v[176:179], v[218:221], v[96:99]
	v_mfma_f32_16x16x32_bf16 v[84:87], v[168:171], v[232:235], v[84:87]
	v_mfma_f32_16x16x32_bf16 v[80:83], v[176:179], v[232:235], v[80:83]
	v_mfma_f32_16x16x32_bf16 v[68:71], v[168:171], v[240:243], v[68:71]
	v_mfma_f32_16x16x32_bf16 v[64:67], v[176:179], v[240:243], v[64:67]
	v_mfma_f32_16x16x32_bf16 v[116:119], v[172:175], v[214:217], v[116:119]
	v_mfma_f32_16x16x32_bf16 v[112:115], v[206:209], v[214:217], v[112:115]
	v_mfma_f32_16x16x32_bf16 v[100:103], v[172:175], v[222:225], v[100:103]
	v_mfma_f32_16x16x32_bf16 v[96:99], v[206:209], v[222:225], v[96:99]
	v_mfma_f32_16x16x32_bf16 v[84:87], v[172:175], v[236:239], v[84:87]
	v_mfma_f32_16x16x32_bf16 v[80:83], v[206:209], v[236:239], v[80:83]
	v_mfma_f32_16x16x32_bf16 v[68:71], v[172:175], v[244:247], v[68:71]
	v_mfma_f32_16x16x32_bf16 v[64:67], v[206:209], v[244:247], v[64:67]
	s_setprio 0
	s_barrier
	s_mov_b32 m0, s35
	v_lshl_add_u64 v[180:181], v[180:181], 0, s[6:7]
	s_add_u32 s10, s10, 0x40080
	ds_read_b128 v[210:213], v136 offset:49152
	ds_read_b128 v[214:217], v136 offset:50176
	ds_read_b128 v[218:221], v136 offset:51200
	ds_read_b128 v[222:225], v136 offset:52224
	ds_read_b128 v[232:235], v136 offset:53248
	ds_read_b128 v[236:239], v136 offset:54272
	ds_read_b128 v[240:243], v136 offset:55296
	ds_read_b128 v[244:247], v136 offset:56320
	global_load_lds_dwordx4 v[180:181], off
	v_lshl_add_u64 v[180:181], v[202:203], 0, s[6:7]
	s_mov_b32 m0, s41
	s_addc_u32 s11, s11, 0
	global_load_lds_dwordx4 v[180:181], off
	s_mov_b32 m0, s47
	s_nop 0
	global_load_lds_dwordx4 v156, s[10:11]
	s_mov_b32 m0, s48
	s_nop 0
	global_load_lds_dwordx4 v152, s[10:11]
	v_lshl_add_u64 v[180:181], v[248:249], 0, s[6:7]
	s_mov_b32 m0, s20
	s_nop 0
	global_load_lds_dwordx4 v[180:181], off
	v_lshl_add_u64 v[180:181], v[250:251], 0, s[6:7]
	s_mov_b32 m0, s21
	s_nop 0
	global_load_lds_dwordx4 v[180:181], off
	s_waitcnt vmcnt(8)
	s_waitcnt lgkmcnt(0)
	s_barrier
	s_setprio 1
	s_waitcnt lgkmcnt(0)
	v_mfma_f32_16x16x32_bf16 v[60:63], v[140:143], v[210:213], v[60:63]
	v_mfma_f32_16x16x32_bf16 v[56:59], v[148:151], v[210:213], v[56:59]
	v_mfma_f32_16x16x32_bf16 v[44:47], v[140:143], v[218:221], v[44:47]
	v_mfma_f32_16x16x32_bf16 v[40:43], v[148:151], v[218:221], v[40:43]
	v_mfma_f32_16x16x32_bf16 v[28:31], v[140:143], v[232:235], v[28:31]
	v_mfma_f32_16x16x32_bf16 v[24:27], v[148:151], v[232:235], v[24:27]
	v_mfma_f32_16x16x32_bf16 v[12:15], v[140:143], v[240:243], v[12:15]
	v_mfma_f32_16x16x32_bf16 v[8:11], v[148:151], v[240:243], v[8:11]
	v_mfma_f32_16x16x32_bf16 v[60:63], v[144:147], v[214:217], v[60:63]
	v_mfma_f32_16x16x32_bf16 v[56:59], v[164:167], v[214:217], v[56:59]
	v_mfma_f32_16x16x32_bf16 v[44:47], v[144:147], v[222:225], v[44:47]
	v_mfma_f32_16x16x32_bf16 v[40:43], v[164:167], v[222:225], v[40:43]
	v_mfma_f32_16x16x32_bf16 v[28:31], v[144:147], v[236:239], v[28:31]
	v_mfma_f32_16x16x32_bf16 v[24:27], v[164:167], v[236:239], v[24:27]
	v_mfma_f32_16x16x32_bf16 v[12:15], v[144:147], v[244:247], v[12:15]
	v_mfma_f32_16x16x32_bf16 v[8:11], v[164:167], v[244:247], v[8:11]
	s_setprio 0
	s_setprio 1
	v_mfma_f32_16x16x32_bf16 v[52:55], v[168:171], v[210:213], v[52:55]
	v_mfma_f32_16x16x32_bf16 v[48:51], v[176:179], v[210:213], v[48:51]
	v_mfma_f32_16x16x32_bf16 v[36:39], v[168:171], v[218:221], v[36:39]
	v_mfma_f32_16x16x32_bf16 v[32:35], v[176:179], v[218:221], v[32:35]
	v_mfma_f32_16x16x32_bf16 v[20:23], v[168:171], v[232:235], v[20:23]
	v_mfma_f32_16x16x32_bf16 v[16:19], v[176:179], v[232:235], v[16:19]
	v_mfma_f32_16x16x32_bf16 v[4:7], v[168:171], v[240:243], v[4:7]
	v_mfma_f32_16x16x32_bf16 v[0:3], v[176:179], v[240:243], v[0:3]
	v_mfma_f32_16x16x32_bf16 v[52:55], v[172:175], v[214:217], v[52:55]
	v_mfma_f32_16x16x32_bf16 v[48:51], v[206:209], v[214:217], v[48:51]
	v_mfma_f32_16x16x32_bf16 v[36:39], v[172:175], v[222:225], v[36:39]
	v_mfma_f32_16x16x32_bf16 v[32:35], v[206:209], v[222:225], v[32:35]
	v_mfma_f32_16x16x32_bf16 v[20:23], v[172:175], v[236:239], v[20:23]
	v_mfma_f32_16x16x32_bf16 v[16:19], v[206:209], v[236:239], v[16:19]
	v_mfma_f32_16x16x32_bf16 v[4:7], v[172:175], v[244:247], v[4:7]
	v_mfma_f32_16x16x32_bf16 v[0:3], v[206:209], v[244:247], v[0:3]
	s_setprio 0
	s_barrier
	s_add_i32 s22, s22, 2
	s_add_u32 s8, s8, 0x100
	s_addc_u32 s9, s9, 0
	s_cmp_gt_u32 s22, 13
	s_cbranch_scc0 .LBB0_611
	s_cmpk_lt_u32 s15, 0x100
	s_cbranch_scc0 .LBB0_614
	s_barrier

.LBB0_661:
	ds_read_b128 v[128:131], v142
	ds_read_b128 v[132:135], v142 offset:1024
	ds_read_b128 v[148:151], v142 offset:2048
	ds_read_b128 v[164:167], v142 offset:3072
	ds_read_b128 v[168:171], v143
	ds_read_b128 v[172:175], v143 offset:1024
	ds_read_b128 v[176:179], v143 offset:2048
	ds_read_b128 v[200:203], v143 offset:3072
	s_add_u32 s2, s0, 0xfffc0080
	s_addc_u32 s3, s1, -1
	s_cmp_eq_u32 s69, 12
	s_cselect_b32 s7, s35, s3
	s_cselect_b32 s6, s65, s2
	s_cselect_b32 s3, s31, s68
	s_cselect_b32 s2, s66, s67
	s_add_i32 m0, s54, 0xc000
	ds_read_b128 v[206:209], v144
	ds_read_b128 v[210:213], v144 offset:1024
	ds_read_b128 v[214:217], v144 offset:2048
	ds_read_b128 v[218:221], v144 offset:3072
	ds_read_b128 v[222:225], v144 offset:4096
	ds_read_b128 v[232:235], v144 offset:5120
	ds_read_b128 v[236:239], v144 offset:6144
	ds_read_b128 v[240:243], v144 offset:7168
	global_load_lds_dwordx4 v160, s[0:1]
	s_add_i32 m0, s54, 0xe000
	s_nop 0
	global_load_lds_dwordx4 v162, s[0:1]
	s_waitcnt vmcnt(8)
	s_waitcnt lgkmcnt(0)
	s_barrier
	s_setprio 1
	s_waitcnt lgkmcnt(0)
	v_mfma_f32_16x16x32_bf16 v[124:127], v[128:131], v[206:209], v[124:127]
	v_mfma_f32_16x16x32_bf16 v[120:123], v[148:151], v[206:209], v[120:123]
	v_mfma_f32_16x16x32_bf16 v[108:111], v[128:131], v[214:217], v[108:111]
	v_mfma_f32_16x16x32_bf16 v[104:107], v[148:151], v[214:217], v[104:107]
	v_mfma_f32_16x16x32_bf16 v[92:95], v[128:131], v[222:225], v[92:95]
	v_mfma_f32_16x16x32_bf16 v[88:91], v[148:151], v[222:225], v[88:91]
	v_mfma_f32_16x16x32_bf16 v[76:79], v[128:131], v[236:239], v[76:79]
	v_mfma_f32_16x16x32_bf16 v[72:75], v[148:151], v[236:239], v[72:75]
	v_mfma_f32_16x16x32_bf16 v[124:127], v[132:135], v[210:213], v[124:127]
	v_mfma_f32_16x16x32_bf16 v[120:123], v[164:167], v[210:213], v[120:123]
	v_mfma_f32_16x16x32_bf16 v[108:111], v[132:135], v[218:221], v[108:111]
	v_mfma_f32_16x16x32_bf16 v[104:107], v[164:167], v[218:221], v[104:107]
	v_mfma_f32_16x16x32_bf16 v[92:95], v[132:135], v[232:235], v[92:95]
	v_mfma_f32_16x16x32_bf16 v[88:91], v[164:167], v[232:235], v[88:91]
	v_mfma_f32_16x16x32_bf16 v[76:79], v[132:135], v[240:243], v[76:79]
	v_mfma_f32_16x16x32_bf16 v[72:75], v[164:167], v[240:243], v[72:75]
	s_setprio 0
	s_setprio 1
	v_mfma_f32_16x16x32_bf16 v[116:119], v[168:171], v[206:209], v[116:119]
	v_mfma_f32_16x16x32_bf16 v[112:115], v[176:179], v[206:209], v[112:115]
	v_mfma_f32_16x16x32_bf16 v[100:103], v[168:171], v[214:217], v[100:103]
	v_mfma_f32_16x16x32_bf16 v[96:99], v[176:179], v[214:217], v[96:99]
	v_mfma_f32_16x16x32_bf16 v[84:87], v[168:171], v[222:225], v[84:87]
	v_mfma_f32_16x16x32_bf16 v[80:83], v[176:179], v[222:225], v[80:83]
	v_mfma_f32_16x16x32_bf16 v[68:71], v[168:171], v[236:239], v[68:71]
	v_mfma_f32_16x16x32_bf16 v[64:67], v[176:179], v[236:239], v[64:67]
	v_mfma_f32_16x16x32_bf16 v[116:119], v[172:175], v[210:213], v[116:119]
	v_mfma_f32_16x16x32_bf16 v[112:115], v[200:203], v[210:213], v[112:115]
	v_mfma_f32_16x16x32_bf16 v[100:103], v[172:175], v[218:221], v[100:103]
	v_mfma_f32_16x16x32_bf16 v[96:99], v[200:203], v[218:221], v[96:99]
	v_mfma_f32_16x16x32_bf16 v[84:87], v[172:175], v[232:235], v[84:87]
	v_mfma_f32_16x16x32_bf16 v[80:83], v[200:203], v[232:235], v[80:83]
	v_mfma_f32_16x16x32_bf16 v[68:71], v[172:175], v[240:243], v[68:71]
	v_mfma_f32_16x16x32_bf16 v[64:67], v[200:203], v[240:243], v[64:67]
	s_setprio 0
	s_barrier
	s_add_i32 s70, s36, s51
	v_lshl_add_u64 v[136:137], s[2:3], 0, v[156:157]
	s_mov_b32 m0, s70
	ds_read_b128 v[206:209], v144 offset:16384
	ds_read_b128 v[210:213], v144 offset:17408
	ds_read_b128 v[214:217], v144 offset:18432
	ds_read_b128 v[218:221], v144 offset:19456
	ds_read_b128 v[222:225], v144 offset:20480
	ds_read_b128 v[232:235], v144 offset:21504
	ds_read_b128 v[236:239], v144 offset:22528
	ds_read_b128 v[240:243], v144 offset:23552
	global_load_lds_dwordx4 v[136:137], off
	s_add_i32 m0, s70, 0x2000
	s_add_u32 s70, s2, 0x40000
	v_lshl_add_u64 v[180:181], s[2:3], 0, v[152:153]
	s_addc_u32 s71, s3, 0
	s_add_i32 s72, s37, s51
	global_load_lds_dwordx4 v[180:181], off
	s_mov_b32 m0, s72
	v_lshl_add_u64 v[246:247], s[6:7], 0, v[154:155]
	global_load_lds_dwordx4 v156, s[70:71]
	s_add_i32 m0, s72, 0x2000
	s_nop 0
	global_load_lds_dwordx4 v152, s[70:71]
	v_lshl_add_u64 v[244:245], s[6:7], 0, v[158:159]
	s_mov_b32 m0, s54
	s_nop 0
	global_load_lds_dwordx4 v[244:245], off
	s_mov_b32 m0, s55
	s_nop 0
	global_load_lds_dwordx4 v[246:247], off
	s_waitcnt vmcnt(8)
	s_waitcnt lgkmcnt(0)
	s_barrier
	s_setprio 1
	s_waitcnt lgkmcnt(0)
	v_mfma_f32_16x16x32_bf16 v[60:63], v[128:131], v[206:209], v[60:63]
	v_mfma_f32_16x16x32_bf16 v[56:59], v[148:151], v[206:209], v[56:59]
	v_mfma_f32_16x16x32_bf16 v[44:47], v[128:131], v[214:217], v[44:47]
	v_mfma_f32_16x16x32_bf16 v[40:43], v[148:151], v[214:217], v[40:43]
	v_mfma_f32_16x16x32_bf16 v[28:31], v[128:131], v[222:225], v[28:31]
	v_mfma_f32_16x16x32_bf16 v[24:27], v[148:151], v[222:225], v[24:27]
	v_mfma_f32_16x16x32_bf16 v[12:15], v[128:131], v[236:239], v[12:15]
	v_mfma_f32_16x16x32_bf16 v[8:11], v[148:151], v[236:239], v[8:11]
	v_mfma_f32_16x16x32_bf16 v[60:63], v[132:135], v[210:213], v[60:63]
	v_mfma_f32_16x16x32_bf16 v[56:59], v[164:167], v[210:213], v[56:59]
	v_mfma_f32_16x16x32_bf16 v[44:47], v[132:135], v[218:221], v[44:47]
	v_mfma_f32_16x16x32_bf16 v[40:43], v[164:167], v[218:221], v[40:43]
	v_mfma_f32_16x16x32_bf16 v[28:31], v[132:135], v[232:235], v[28:31]
	v_mfma_f32_16x16x32_bf16 v[24:27], v[164:167], v[232:235], v[24:27]
	v_mfma_f32_16x16x32_bf16 v[12:15], v[132:135], v[240:243], v[12:15]
	v_mfma_f32_16x16x32_bf16 v[8:11], v[164:167], v[240:243], v[8:11]
	s_setprio 0
	s_setprio 1
	v_mfma_f32_16x16x32_bf16 v[52:55], v[168:171], v[206:209], v[52:55]
	v_mfma_f32_16x16x32_bf16 v[48:51], v[176:179], v[206:209], v[48:51]
	v_mfma_f32_16x16x32_bf16 v[36:39], v[168:171], v[214:217], v[36:39]
	v_mfma_f32_16x16x32_bf16 v[32:35], v[176:179], v[214:217], v[32:35]
	v_mfma_f32_16x16x32_bf16 v[20:23], v[168:171], v[222:225], v[20:23]
	v_mfma_f32_16x16x32_bf16 v[16:19], v[176:179], v[222:225], v[16:19]
	v_mfma_f32_16x16x32_bf16 v[4:7], v[168:171], v[236:239], v[4:7]
	v_mfma_f32_16x16x32_bf16 v[0:3], v[176:179], v[236:239], v[0:3]
	v_mfma_f32_16x16x32_bf16 v[52:55], v[172:175], v[210:213], v[52:55]
	v_mfma_f32_16x16x32_bf16 v[48:51], v[200:203], v[210:213], v[48:51]
	v_mfma_f32_16x16x32_bf16 v[36:39], v[172:175], v[218:221], v[36:39]
	v_mfma_f32_16x16x32_bf16 v[32:35], v[200:203], v[218:221], v[32:35]
	v_mfma_f32_16x16x32_bf16 v[20:23], v[172:175], v[232:235], v[20:23]
	v_mfma_f32_16x16x32_bf16 v[16:19], v[200:203], v[232:235], v[16:19]
	v_mfma_f32_16x16x32_bf16 v[4:7], v[172:175], v[240:243], v[4:7]
	v_mfma_f32_16x16x32_bf16 v[0:3], v[200:203], v[240:243], v[0:3]
	s_setprio 0
	s_barrier
	v_add_u32_e32 v147, s45, v140
	ds_read_b128 v[128:131], v147
	ds_read_b128 v[132:135], v147 offset:1024
	ds_read_b128 v[148:151], v147 offset:2048
	ds_read_b128 v[164:167], v147 offset:3072
	v_add_u32_e32 v147, s46, v140
	ds_read_b128 v[168:171], v147
	ds_read_b128 v[172:175], v147 offset:1024
	ds_read_b128 v[176:179], v147 offset:2048
	ds_read_b128 v[200:203], v147 offset:3072
	s_add_u32 s6, s6, 0x40000
	s_addc_u32 s7, s7, 0
	s_mov_b32 m0, s56
	ds_read_b128 v[206:209], v144 offset:32768
	ds_read_b128 v[210:213], v144 offset:33792
	ds_read_b128 v[214:217], v144 offset:34816
	ds_read_b128 v[218:221], v144 offset:35840
	ds_read_b128 v[222:225], v144 offset:36864
	ds_read_b128 v[232:235], v144 offset:37888
	ds_read_b128 v[236:239], v144 offset:38912
	ds_read_b128 v[240:243], v144 offset:39936
	global_load_lds_dwordx4 v158, s[6:7]
	s_mov_b32 m0, s57
	s_nop 0
	global_load_lds_dwordx4 v154, s[6:7]
	s_waitcnt vmcnt(8)
	s_waitcnt lgkmcnt(0)
	s_barrier
	s_setprio 1
	s_waitcnt lgkmcnt(0)
	v_mfma_f32_16x16x32_bf16 v[124:127], v[128:131], v[206:209], v[124:127]
	v_mfma_f32_16x16x32_bf16 v[120:123], v[148:151], v[206:209], v[120:123]
	v_mfma_f32_16x16x32_bf16 v[108:111], v[128:131], v[214:217], v[108:111]
	v_mfma_f32_16x16x32_bf16 v[104:107], v[148:151], v[214:217], v[104:107]
	v_mfma_f32_16x16x32_bf16 v[92:95], v[128:131], v[222:225], v[92:95]
	v_mfma_f32_16x16x32_bf16 v[88:91], v[148:151], v[222:225], v[88:91]
	v_mfma_f32_16x16x32_bf16 v[76:79], v[128:131], v[236:239], v[76:79]
	v_mfma_f32_16x16x32_bf16 v[72:75], v[148:151], v[236:239], v[72:75]
	v_mfma_f32_16x16x32_bf16 v[124:127], v[132:135], v[210:213], v[124:127]
	v_mfma_f32_16x16x32_bf16 v[120:123], v[164:167], v[210:213], v[120:123]
	v_mfma_f32_16x16x32_bf16 v[108:111], v[132:135], v[218:221], v[108:111]
	v_mfma_f32_16x16x32_bf16 v[104:107], v[164:167], v[218:221], v[104:107]
	v_mfma_f32_16x16x32_bf16 v[92:95], v[132:135], v[232:235], v[92:95]
	v_mfma_f32_16x16x32_bf16 v[88:91], v[164:167], v[232:235], v[88:91]
	v_mfma_f32_16x16x32_bf16 v[76:79], v[132:135], v[240:243], v[76:79]
	v_mfma_f32_16x16x32_bf16 v[72:75], v[164:167], v[240:243], v[72:75]
	s_setprio 0
	s_setprio 1
	v_mfma_f32_16x16x32_bf16 v[116:119], v[168:171], v[206:209], v[116:119]
	v_mfma_f32_16x16x32_bf16 v[112:115], v[176:179], v[206:209], v[112:115]
	v_mfma_f32_16x16x32_bf16 v[100:103], v[168:171], v[214:217], v[100:103]
	v_mfma_f32_16x16x32_bf16 v[96:99], v[176:179], v[214:217], v[96:99]
	v_mfma_f32_16x16x32_bf16 v[84:87], v[168:171], v[222:225], v[84:87]
	v_mfma_f32_16x16x32_bf16 v[80:83], v[176:179], v[222:225], v[80:83]
	v_mfma_f32_16x16x32_bf16 v[68:71], v[168:171], v[236:239], v[68:71]
	v_mfma_f32_16x16x32_bf16 v[64:67], v[176:179], v[236:239], v[64:67]
	v_mfma_f32_16x16x32_bf16 v[116:119], v[172:175], v[210:213], v[116:119]
	v_mfma_f32_16x16x32_bf16 v[112:115], v[200:203], v[210:213], v[112:115]
	v_mfma_f32_16x16x32_bf16 v[100:103], v[172:175], v[218:221], v[100:103]
	v_mfma_f32_16x16x32_bf16 v[96:99], v[200:203], v[218:221], v[96:99]
	v_mfma_f32_16x16x32_bf16 v[84:87], v[172:175], v[232:235], v[84:87]
	v_mfma_f32_16x16x32_bf16 v[80:83], v[200:203], v[232:235], v[80:83]
	v_mfma_f32_16x16x32_bf16 v[68:71], v[172:175], v[240:243], v[68:71]
	v_mfma_f32_16x16x32_bf16 v[64:67], v[200:203], v[240:243], v[64:67]
	s_setprio 0
	s_barrier
	s_add_i32 s6, s45, s51
	v_lshl_add_u64 v[136:137], v[136:137], 0, s[22:23]
	s_mov_b32 m0, s6
	ds_read_b128 v[206:209], v144 offset:49152
	ds_read_b128 v[210:213], v144 offset:50176
	ds_read_b128 v[214:217], v144 offset:51200
	ds_read_b128 v[218:221], v144 offset:52224
	ds_read_b128 v[222:225], v144 offset:53248
	ds_read_b128 v[232:235], v144 offset:54272
	ds_read_b128 v[236:239], v144 offset:55296
	ds_read_b128 v[240:243], v144 offset:56320
	global_load_lds_dwordx4 v[136:137], off
	s_add_i32 m0, s6, 0x2000
	s_add_u32 s2, s2, 0x40080
	v_lshl_add_u64 v[136:137], v[180:181], 0, s[22:23]
	s_addc_u32 s3, s3, 0
	s_add_i32 s6, s46, s51
	global_load_lds_dwordx4 v[136:137], off
	s_mov_b32 m0, s6
	s_nop 0
	global_load_lds_dwordx4 v156, s[2:3]
	s_add_i32 m0, s6, 0x2000
	s_nop 0
	global_load_lds_dwordx4 v152, s[2:3]
	v_lshl_add_u64 v[136:137], v[244:245], 0, s[22:23]
	s_mov_b32 m0, s59
	s_nop 0
	global_load_lds_dwordx4 v[136:137], off
	v_lshl_add_u64 v[136:137], v[246:247], 0, s[22:23]
	s_mov_b32 m0, s60
	s_nop 0
	global_load_lds_dwordx4 v[136:137], off
	s_waitcnt vmcnt(8)
	s_waitcnt lgkmcnt(0)
	s_barrier
	s_setprio 1
	s_waitcnt lgkmcnt(0)
	v_mfma_f32_16x16x32_bf16 v[60:63], v[128:131], v[206:209], v[60:63]
	v_mfma_f32_16x16x32_bf16 v[56:59], v[148:151], v[206:209], v[56:59]
	v_mfma_f32_16x16x32_bf16 v[44:47], v[128:131], v[214:217], v[44:47]
	v_mfma_f32_16x16x32_bf16 v[40:43], v[148:151], v[214:217], v[40:43]
	v_mfma_f32_16x16x32_bf16 v[28:31], v[128:131], v[222:225], v[28:31]
	v_mfma_f32_16x16x32_bf16 v[24:27], v[148:151], v[222:225], v[24:27]
	v_mfma_f32_16x16x32_bf16 v[12:15], v[128:131], v[236:239], v[12:15]
	v_mfma_f32_16x16x32_bf16 v[8:11], v[148:151], v[236:239], v[8:11]
	v_mfma_f32_16x16x32_bf16 v[60:63], v[132:135], v[210:213], v[60:63]
	v_mfma_f32_16x16x32_bf16 v[56:59], v[164:167], v[210:213], v[56:59]
	v_mfma_f32_16x16x32_bf16 v[44:47], v[132:135], v[218:221], v[44:47]
	v_mfma_f32_16x16x32_bf16 v[40:43], v[164:167], v[218:221], v[40:43]
	v_mfma_f32_16x16x32_bf16 v[28:31], v[132:135], v[232:235], v[28:31]
	v_mfma_f32_16x16x32_bf16 v[24:27], v[164:167], v[232:235], v[24:27]
	v_mfma_f32_16x16x32_bf16 v[12:15], v[132:135], v[240:243], v[12:15]
	v_mfma_f32_16x16x32_bf16 v[8:11], v[164:167], v[240:243], v[8:11]
	s_setprio 0
	s_setprio 1
	v_mfma_f32_16x16x32_bf16 v[52:55], v[168:171], v[206:209], v[52:55]
	v_mfma_f32_16x16x32_bf16 v[48:51], v[176:179], v[206:209], v[48:51]
	v_mfma_f32_16x16x32_bf16 v[36:39], v[168:171], v[214:217], v[36:39]
	v_mfma_f32_16x16x32_bf16 v[32:35], v[176:179], v[214:217], v[32:35]
	v_mfma_f32_16x16x32_bf16 v[20:23], v[168:171], v[222:225], v[20:23]
	v_mfma_f32_16x16x32_bf16 v[16:19], v[176:179], v[222:225], v[16:19]
	v_mfma_f32_16x16x32_bf16 v[4:7], v[168:171], v[236:239], v[4:7]
	v_mfma_f32_16x16x32_bf16 v[0:3], v[176:179], v[236:239], v[0:3]
	v_mfma_f32_16x16x32_bf16 v[52:55], v[172:175], v[210:213], v[52:55]
	v_mfma_f32_16x16x32_bf16 v[48:51], v[200:203], v[210:213], v[48:51]
	v_mfma_f32_16x16x32_bf16 v[36:39], v[172:175], v[218:221], v[36:39]
	v_mfma_f32_16x16x32_bf16 v[32:35], v[200:203], v[218:221], v[32:35]
	v_mfma_f32_16x16x32_bf16 v[20:23], v[172:175], v[232:235], v[20:23]
	v_mfma_f32_16x16x32_bf16 v[16:19], v[200:203], v[232:235], v[16:19]
	v_mfma_f32_16x16x32_bf16 v[4:7], v[172:175], v[240:243], v[4:7]
	v_mfma_f32_16x16x32_bf16 v[0:3], v[200:203], v[240:243], v[0:3]
	s_setprio 0
	s_barrier
	s_add_i32 s69, s69, 2
	s_add_u32 s0, s0, 0x100
	s_addc_u32 s1, s1, 0
	s_add_u32 s67, s67, 0x100
	s_addc_u32 s68, s68, 0
	s_cmp_gt_u32 s69, 13
	s_cbranch_scc0 .LBB0_661
	s_and_b64 vcc, exec, s[28:29]
	s_cbranch_vccz .LBB0_664
	s_barrier

.LBB0_684:
	ds_read_b128 v[146:149], v141
	ds_read_b128 v[150:153], v141 offset:1024
	ds_read_b128 v[154:157], v141 offset:2048
	ds_read_b128 v[158:161], v141 offset:3072
	ds_read_b128 v[162:165], v142
	ds_read_b128 v[166:169], v142 offset:1024
	ds_read_b128 v[170:173], v142 offset:2048
	ds_read_b128 v[174:177], v142 offset:3072
	s_add_u32 s14, s12, 0xf8a00080
	s_addc_u32 s15, s13, -1
	s_cmp_lg_u32 s30, 60
	s_cselect_b32 s14, s14, 0
	s_cselect_b32 s15, s15, 0
	s_add_u32 s16, s2, s14
	s_addc_u32 s17, s3, s15
	s_add_u32 s14, s0, s14
	s_addc_u32 s15, s1, s15
	s_mov_b32 m0, s31
	v_lshl_add_u64 v[218:219], v[136:137], 0, s[12:13]
	ds_read_b128 v[178:181], v143
	ds_read_b128 v[184:187], v143 offset:1024
	ds_read_b128 v[188:191], v143 offset:2048
	ds_read_b128 v[194:197], v143 offset:3072
	ds_read_b128 v[200:203], v143 offset:4096
	ds_read_b128 v[206:209], v143 offset:5120
	ds_read_b128 v[210:213], v143 offset:6144
	ds_read_b128 v[214:217], v143 offset:7168
	global_load_lds_dwordx4 v[218:219], off
	v_lshl_add_u64 v[218:219], v[138:139], 0, s[12:13]
	s_mov_b32 m0, s33
	s_nop 0
	global_load_lds_dwordx4 v[218:219], off
	s_waitcnt vmcnt(8)
	s_waitcnt lgkmcnt(0)
	s_barrier
	s_setprio 1
	s_waitcnt lgkmcnt(0)
	v_mfma_f32_16x16x32_bf16 v[124:127], v[146:149], v[178:181], v[124:127]
	v_mfma_f32_16x16x32_bf16 v[120:123], v[154:157], v[178:181], v[120:123]
	v_mfma_f32_16x16x32_bf16 v[108:111], v[146:149], v[188:191], v[108:111]
	v_mfma_f32_16x16x32_bf16 v[104:107], v[154:157], v[188:191], v[104:107]
	v_mfma_f32_16x16x32_bf16 v[92:95], v[146:149], v[200:203], v[92:95]
	v_mfma_f32_16x16x32_bf16 v[88:91], v[154:157], v[200:203], v[88:91]
	v_mfma_f32_16x16x32_bf16 v[76:79], v[146:149], v[210:213], v[76:79]
	v_mfma_f32_16x16x32_bf16 v[72:75], v[154:157], v[210:213], v[72:75]
	v_mfma_f32_16x16x32_bf16 v[124:127], v[150:153], v[184:187], v[124:127]
	v_mfma_f32_16x16x32_bf16 v[120:123], v[158:161], v[184:187], v[120:123]
	v_mfma_f32_16x16x32_bf16 v[108:111], v[150:153], v[194:197], v[108:111]
	v_mfma_f32_16x16x32_bf16 v[104:107], v[158:161], v[194:197], v[104:107]
	v_mfma_f32_16x16x32_bf16 v[92:95], v[150:153], v[206:209], v[92:95]
	v_mfma_f32_16x16x32_bf16 v[88:91], v[158:161], v[206:209], v[88:91]
	v_mfma_f32_16x16x32_bf16 v[76:79], v[150:153], v[214:217], v[76:79]
	v_mfma_f32_16x16x32_bf16 v[72:75], v[158:161], v[214:217], v[72:75]
	s_setprio 0
	s_setprio 1
	v_mfma_f32_16x16x32_bf16 v[116:119], v[162:165], v[178:181], v[116:119]
	v_mfma_f32_16x16x32_bf16 v[112:115], v[170:173], v[178:181], v[112:115]
	v_mfma_f32_16x16x32_bf16 v[100:103], v[162:165], v[188:191], v[100:103]
	v_mfma_f32_16x16x32_bf16 v[96:99], v[170:173], v[188:191], v[96:99]
	v_mfma_f32_16x16x32_bf16 v[84:87], v[162:165], v[200:203], v[84:87]
	v_mfma_f32_16x16x32_bf16 v[80:83], v[170:173], v[200:203], v[80:83]
	v_mfma_f32_16x16x32_bf16 v[68:71], v[162:165], v[210:213], v[68:71]
	v_mfma_f32_16x16x32_bf16 v[64:67], v[170:173], v[210:213], v[64:67]
	v_mfma_f32_16x16x32_bf16 v[116:119], v[166:169], v[184:187], v[116:119]
	v_mfma_f32_16x16x32_bf16 v[112:115], v[174:177], v[184:187], v[112:115]
	v_mfma_f32_16x16x32_bf16 v[100:103], v[166:169], v[194:197], v[100:103]
	v_mfma_f32_16x16x32_bf16 v[96:99], v[174:177], v[194:197], v[96:99]
	v_mfma_f32_16x16x32_bf16 v[84:87], v[166:169], v[206:209], v[84:87]
	v_mfma_f32_16x16x32_bf16 v[80:83], v[174:177], v[206:209], v[80:83]
	v_mfma_f32_16x16x32_bf16 v[68:71], v[166:169], v[214:217], v[68:71]
	v_mfma_f32_16x16x32_bf16 v[64:67], v[174:177], v[214:217], v[64:67]
	s_setprio 0
	s_barrier
	s_mov_b32 m0, s34
	v_lshl_add_u64 v[218:219], s[14:15], 0, v[132:133]
	s_add_u32 s48, s14, 0x100000
	ds_read_b128 v[178:181], v143 offset:16384
	ds_read_b128 v[184:187], v143 offset:17408
	ds_read_b128 v[188:191], v143 offset:18432
	ds_read_b128 v[194:197], v143 offset:19456
	ds_read_b128 v[200:203], v143 offset:20480
	ds_read_b128 v[206:209], v143 offset:21504
	ds_read_b128 v[210:213], v143 offset:22528
	ds_read_b128 v[214:217], v143 offset:23552
	global_load_lds_dwordx4 v[218:219], off
	v_lshl_add_u64 v[220:221], s[14:15], 0, v[128:129]
	s_mov_b32 m0, s35
	s_addc_u32 s49, s15, 0
	global_load_lds_dwordx4 v[220:221], off
	s_mov_b32 m0, s36
	v_lshl_add_u64 v[224:225], s[16:17], 0, v[130:131]
	global_load_lds_dwordx4 v132, s[48:49]
	s_mov_b32 m0, s37
	s_nop 0
	global_load_lds_dwordx4 v128, s[48:49]
	v_lshl_add_u64 v[222:223], s[16:17], 0, v[134:135]
	s_mov_b32 m0, s19
	s_nop 0
	global_load_lds_dwordx4 v[222:223], off
	s_mov_b32 m0, s20
	s_nop 0
	global_load_lds_dwordx4 v[224:225], off
	s_waitcnt vmcnt(8)
	s_waitcnt lgkmcnt(0)
	s_barrier
	s_setprio 1
	s_waitcnt lgkmcnt(0)
	v_mfma_f32_16x16x32_bf16 v[60:63], v[146:149], v[178:181], v[60:63]
	v_mfma_f32_16x16x32_bf16 v[56:59], v[154:157], v[178:181], v[56:59]
	v_mfma_f32_16x16x32_bf16 v[44:47], v[146:149], v[188:191], v[44:47]
	v_mfma_f32_16x16x32_bf16 v[40:43], v[154:157], v[188:191], v[40:43]
	v_mfma_f32_16x16x32_bf16 v[28:31], v[146:149], v[200:203], v[28:31]
	v_mfma_f32_16x16x32_bf16 v[24:27], v[154:157], v[200:203], v[24:27]
	v_mfma_f32_16x16x32_bf16 v[12:15], v[146:149], v[210:213], v[12:15]
	v_mfma_f32_16x16x32_bf16 v[8:11], v[154:157], v[210:213], v[8:11]
	v_mfma_f32_16x16x32_bf16 v[60:63], v[150:153], v[184:187], v[60:63]
	v_mfma_f32_16x16x32_bf16 v[56:59], v[158:161], v[184:187], v[56:59]
	v_mfma_f32_16x16x32_bf16 v[44:47], v[150:153], v[194:197], v[44:47]
	v_mfma_f32_16x16x32_bf16 v[40:43], v[158:161], v[194:197], v[40:43]
	v_mfma_f32_16x16x32_bf16 v[28:31], v[150:153], v[206:209], v[28:31]
	v_mfma_f32_16x16x32_bf16 v[24:27], v[158:161], v[206:209], v[24:27]
	v_mfma_f32_16x16x32_bf16 v[12:15], v[150:153], v[214:217], v[12:15]
	v_mfma_f32_16x16x32_bf16 v[8:11], v[158:161], v[214:217], v[8:11]
	s_setprio 0
	s_setprio 1
	v_mfma_f32_16x16x32_bf16 v[52:55], v[162:165], v[178:181], v[52:55]
	v_mfma_f32_16x16x32_bf16 v[48:51], v[170:173], v[178:181], v[48:51]
	v_mfma_f32_16x16x32_bf16 v[36:39], v[162:165], v[188:191], v[36:39]
	v_mfma_f32_16x16x32_bf16 v[32:35], v[170:173], v[188:191], v[32:35]
	v_mfma_f32_16x16x32_bf16 v[20:23], v[162:165], v[200:203], v[20:23]
	v_mfma_f32_16x16x32_bf16 v[16:19], v[170:173], v[200:203], v[16:19]
	v_mfma_f32_16x16x32_bf16 v[4:7], v[162:165], v[210:213], v[4:7]
	v_mfma_f32_16x16x32_bf16 v[0:3], v[170:173], v[210:213], v[0:3]
	v_mfma_f32_16x16x32_bf16 v[52:55], v[166:169], v[184:187], v[52:55]
	v_mfma_f32_16x16x32_bf16 v[48:51], v[174:177], v[184:187], v[48:51]
	v_mfma_f32_16x16x32_bf16 v[36:39], v[166:169], v[194:197], v[36:39]
	v_mfma_f32_16x16x32_bf16 v[32:35], v[174:177], v[194:197], v[32:35]
	v_mfma_f32_16x16x32_bf16 v[20:23], v[166:169], v[206:209], v[20:23]
	v_mfma_f32_16x16x32_bf16 v[16:19], v[174:177], v[206:209], v[16:19]
	v_mfma_f32_16x16x32_bf16 v[4:7], v[166:169], v[214:217], v[4:7]
	v_mfma_f32_16x16x32_bf16 v[0:3], v[174:177], v[214:217], v[0:3]
	s_setprio 0
	s_barrier
	ds_read_b128 v[146:149], v144
	ds_read_b128 v[150:153], v144 offset:1024
	ds_read_b128 v[154:157], v144 offset:2048
	ds_read_b128 v[158:161], v144 offset:3072
	ds_read_b128 v[162:165], v145
	ds_read_b128 v[166:169], v145 offset:1024
	ds_read_b128 v[170:173], v145 offset:2048
	ds_read_b128 v[174:177], v145 offset:3072
	s_add_u32 s16, s16, 0x100000
	s_addc_u32 s17, s17, 0
	s_mov_b32 m0, s21
	ds_read_b128 v[178:181], v143 offset:32768
	ds_read_b128 v[184:187], v143 offset:33792
	ds_read_b128 v[188:191], v143 offset:34816
	ds_read_b128 v[194:197], v143 offset:35840
	ds_read_b128 v[200:203], v143 offset:36864
	ds_read_b128 v[206:209], v143 offset:37888
	ds_read_b128 v[210:213], v143 offset:38912
	ds_read_b128 v[214:217], v143 offset:39936
	global_load_lds_dwordx4 v134, s[16:17]
	s_mov_b32 m0, s22
	s_nop 0
	global_load_lds_dwordx4 v130, s[16:17]
	s_waitcnt vmcnt(8)
	s_waitcnt lgkmcnt(0)
	s_barrier
	s_setprio 1
	s_waitcnt lgkmcnt(0)
	v_mfma_f32_16x16x32_bf16 v[124:127], v[146:149], v[178:181], v[124:127]
	v_mfma_f32_16x16x32_bf16 v[120:123], v[154:157], v[178:181], v[120:123]
	v_mfma_f32_16x16x32_bf16 v[108:111], v[146:149], v[188:191], v[108:111]
	v_mfma_f32_16x16x32_bf16 v[104:107], v[154:157], v[188:191], v[104:107]
	v_mfma_f32_16x16x32_bf16 v[92:95], v[146:149], v[200:203], v[92:95]
	v_mfma_f32_16x16x32_bf16 v[88:91], v[154:157], v[200:203], v[88:91]
	v_mfma_f32_16x16x32_bf16 v[76:79], v[146:149], v[210:213], v[76:79]
	v_mfma_f32_16x16x32_bf16 v[72:75], v[154:157], v[210:213], v[72:75]
	v_mfma_f32_16x16x32_bf16 v[124:127], v[150:153], v[184:187], v[124:127]
	v_mfma_f32_16x16x32_bf16 v[120:123], v[158:161], v[184:187], v[120:123]
	v_mfma_f32_16x16x32_bf16 v[108:111], v[150:153], v[194:197], v[108:111]
	v_mfma_f32_16x16x32_bf16 v[104:107], v[158:161], v[194:197], v[104:107]
	v_mfma_f32_16x16x32_bf16 v[92:95], v[150:153], v[206:209], v[92:95]
	v_mfma_f32_16x16x32_bf16 v[88:91], v[158:161], v[206:209], v[88:91]
	v_mfma_f32_16x16x32_bf16 v[76:79], v[150:153], v[214:217], v[76:79]
	v_mfma_f32_16x16x32_bf16 v[72:75], v[158:161], v[214:217], v[72:75]
	s_setprio 0
	s_setprio 1
	v_mfma_f32_16x16x32_bf16 v[116:119], v[162:165], v[178:181], v[116:119]
	v_mfma_f32_16x16x32_bf16 v[112:115], v[170:173], v[178:181], v[112:115]
	v_mfma_f32_16x16x32_bf16 v[100:103], v[162:165], v[188:191], v[100:103]
	v_mfma_f32_16x16x32_bf16 v[96:99], v[170:173], v[188:191], v[96:99]
	v_mfma_f32_16x16x32_bf16 v[84:87], v[162:165], v[200:203], v[84:87]
	v_mfma_f32_16x16x32_bf16 v[80:83], v[170:173], v[200:203], v[80:83]
	v_mfma_f32_16x16x32_bf16 v[68:71], v[162:165], v[210:213], v[68:71]
	v_mfma_f32_16x16x32_bf16 v[64:67], v[170:173], v[210:213], v[64:67]
	v_mfma_f32_16x16x32_bf16 v[116:119], v[166:169], v[184:187], v[116:119]
	v_mfma_f32_16x16x32_bf16 v[112:115], v[174:177], v[184:187], v[112:115]
	v_mfma_f32_16x16x32_bf16 v[100:103], v[166:169], v[194:197], v[100:103]
	v_mfma_f32_16x16x32_bf16 v[96:99], v[174:177], v[194:197], v[96:99]
	v_mfma_f32_16x16x32_bf16 v[84:87], v[166:169], v[206:209], v[84:87]
	v_mfma_f32_16x16x32_bf16 v[80:83], v[174:177], v[206:209], v[80:83]
	v_mfma_f32_16x16x32_bf16 v[68:71], v[166:169], v[214:217], v[68:71]
	v_mfma_f32_16x16x32_bf16 v[64:67], v[174:177], v[214:217], v[64:67]
	s_setprio 0
	s_barrier
	s_mov_b32 m0, s41
	v_lshl_add_u64 v[218:219], v[218:219], 0, s[6:7]
	s_add_u32 s14, s14, 0x100080
	ds_read_b128 v[178:181], v143 offset:49152
	ds_read_b128 v[184:187], v143 offset:50176
	ds_read_b128 v[188:191], v143 offset:51200
	ds_read_b128 v[194:197], v143 offset:52224
	ds_read_b128 v[200:203], v143 offset:53248
	ds_read_b128 v[206:209], v143 offset:54272
	ds_read_b128 v[210:213], v143 offset:55296
	ds_read_b128 v[214:217], v143 offset:56320
	global_load_lds_dwordx4 v[218:219], off
	v_lshl_add_u64 v[218:219], v[220:221], 0, s[6:7]
	s_mov_b32 m0, s44
	s_addc_u32 s15, s15, 0
	global_load_lds_dwordx4 v[218:219], off
	s_mov_b32 m0, s45
	s_nop 0
	global_load_lds_dwordx4 v132, s[14:15]
	s_mov_b32 m0, s46
	s_nop 0
	global_load_lds_dwordx4 v128, s[14:15]
	v_lshl_add_u64 v[218:219], v[222:223], 0, s[6:7]
	s_mov_b32 m0, s28
	s_nop 0
	global_load_lds_dwordx4 v[218:219], off
	v_lshl_add_u64 v[218:219], v[224:225], 0, s[6:7]
	s_mov_b32 m0, s29
	s_nop 0
	global_load_lds_dwordx4 v[218:219], off
	s_waitcnt vmcnt(8)
	s_waitcnt lgkmcnt(0)
	s_barrier
	s_setprio 1
	s_waitcnt lgkmcnt(0)
	v_mfma_f32_16x16x32_bf16 v[60:63], v[146:149], v[178:181], v[60:63]
	v_mfma_f32_16x16x32_bf16 v[56:59], v[154:157], v[178:181], v[56:59]
	v_mfma_f32_16x16x32_bf16 v[44:47], v[146:149], v[188:191], v[44:47]
	v_mfma_f32_16x16x32_bf16 v[40:43], v[154:157], v[188:191], v[40:43]
	v_mfma_f32_16x16x32_bf16 v[28:31], v[146:149], v[200:203], v[28:31]
	v_mfma_f32_16x16x32_bf16 v[24:27], v[154:157], v[200:203], v[24:27]
	v_mfma_f32_16x16x32_bf16 v[12:15], v[146:149], v[210:213], v[12:15]
	v_mfma_f32_16x16x32_bf16 v[8:11], v[154:157], v[210:213], v[8:11]
	v_mfma_f32_16x16x32_bf16 v[60:63], v[150:153], v[184:187], v[60:63]
	v_mfma_f32_16x16x32_bf16 v[56:59], v[158:161], v[184:187], v[56:59]
	v_mfma_f32_16x16x32_bf16 v[44:47], v[150:153], v[194:197], v[44:47]
	v_mfma_f32_16x16x32_bf16 v[40:43], v[158:161], v[194:197], v[40:43]
	v_mfma_f32_16x16x32_bf16 v[28:31], v[150:153], v[206:209], v[28:31]
	v_mfma_f32_16x16x32_bf16 v[24:27], v[158:161], v[206:209], v[24:27]
	v_mfma_f32_16x16x32_bf16 v[12:15], v[150:153], v[214:217], v[12:15]
	v_mfma_f32_16x16x32_bf16 v[8:11], v[158:161], v[214:217], v[8:11]
	s_setprio 0
	s_setprio 1
	v_mfma_f32_16x16x32_bf16 v[52:55], v[162:165], v[178:181], v[52:55]
	v_mfma_f32_16x16x32_bf16 v[48:51], v[170:173], v[178:181], v[48:51]
	v_mfma_f32_16x16x32_bf16 v[36:39], v[162:165], v[188:191], v[36:39]
	v_mfma_f32_16x16x32_bf16 v[32:35], v[170:173], v[188:191], v[32:35]
	v_mfma_f32_16x16x32_bf16 v[20:23], v[162:165], v[200:203], v[20:23]
	v_mfma_f32_16x16x32_bf16 v[16:19], v[170:173], v[200:203], v[16:19]
	v_mfma_f32_16x16x32_bf16 v[4:7], v[162:165], v[210:213], v[4:7]
	v_mfma_f32_16x16x32_bf16 v[0:3], v[170:173], v[210:213], v[0:3]
	v_mfma_f32_16x16x32_bf16 v[52:55], v[166:169], v[184:187], v[52:55]
	v_mfma_f32_16x16x32_bf16 v[48:51], v[174:177], v[184:187], v[48:51]
	v_mfma_f32_16x16x32_bf16 v[36:39], v[166:169], v[194:197], v[36:39]
	v_mfma_f32_16x16x32_bf16 v[32:35], v[174:177], v[194:197], v[32:35]
	v_mfma_f32_16x16x32_bf16 v[20:23], v[166:169], v[206:209], v[20:23]
	v_mfma_f32_16x16x32_bf16 v[16:19], v[174:177], v[206:209], v[16:19]
	v_mfma_f32_16x16x32_bf16 v[4:7], v[166:169], v[214:217], v[4:7]
	v_mfma_f32_16x16x32_bf16 v[0:3], v[174:177], v[214:217], v[0:3]
	s_setprio 0
	s_barrier
	s_add_i32 s30, s30, 2
	s_add_u32 s12, s12, 0x100
	s_addc_u32 s13, s13, 0
	s_cmp_gt_u32 s30, 61
	s_cbranch_scc0 .LBB0_684
	s_cmpk_lt_u32 s18, 0x100
	s_cbranch_scc0 .LBB0_687
	s_barrier

.LBB0_768:
	ds_read_b128 v[32:35], v232
	ds_read_b128 v[36:39], v232 offset:1024
	ds_read_b128 v[40:43], v232 offset:2048
	ds_read_b128 v[44:47], v232 offset:3072
	ds_read_b128 v[48:51], v233
	ds_read_b128 v[56:59], v233 offset:1024
	ds_read_b128 v[64:67], v233 offset:2048
	ds_read_b128 v[68:71], v233 offset:3072
	s_add_u32 s12, s10, 0xfffc0080
	s_addc_u32 s13, s11, -1
	s_cmp_eq_u32 s68, 12
	s_cselect_b32 s45, s1, s13
	s_cselect_b32 s44, s3, s12
	s_cselect_b32 s13, s29, s67
	s_cselect_b32 s12, s31, s33
	s_add_i32 m0, s50, 0xc000
	ds_read_b128 v[160:163], v234
	ds_read_b128 v[164:167], v234 offset:1024
	ds_read_b128 v[168:171], v234 offset:2048
	ds_read_b128 v[172:175], v234 offset:3072
	ds_read_b128 v[176:179], v234 offset:4096
	ds_read_b128 v[180:183], v234 offset:5120
	ds_read_b128 v[184:187], v234 offset:6144
	ds_read_b128 v[188:191], v234 offset:7168
	global_load_lds_dwordx4 v208, s[10:11]
	s_add_i32 m0, s50, 0xe000
	s_nop 0
	global_load_lds_dwordx4 v210, s[10:11]
	s_waitcnt vmcnt(8)
	s_waitcnt lgkmcnt(0)
	s_barrier
	s_setprio 1
	s_waitcnt lgkmcnt(0)
	v_mfma_f32_16x16x32_bf16 v[156:159], v[32:35], v[160:163], v[156:159]
	v_mfma_f32_16x16x32_bf16 v[152:155], v[40:43], v[160:163], v[152:155]
	v_mfma_f32_16x16x32_bf16 v[140:143], v[32:35], v[168:171], v[140:143]
	v_mfma_f32_16x16x32_bf16 v[136:139], v[40:43], v[168:171], v[136:139]
	v_mfma_f32_16x16x32_bf16 v[124:127], v[32:35], v[176:179], v[124:127]
	v_mfma_f32_16x16x32_bf16 v[120:123], v[40:43], v[176:179], v[120:123]
	v_mfma_f32_16x16x32_bf16 v[108:111], v[32:35], v[184:187], v[108:111]
	v_mfma_f32_16x16x32_bf16 v[104:107], v[40:43], v[184:187], v[104:107]
	v_mfma_f32_16x16x32_bf16 v[156:159], v[36:39], v[164:167], v[156:159]
	v_mfma_f32_16x16x32_bf16 v[152:155], v[44:47], v[164:167], v[152:155]
	v_mfma_f32_16x16x32_bf16 v[140:143], v[36:39], v[172:175], v[140:143]
	v_mfma_f32_16x16x32_bf16 v[136:139], v[44:47], v[172:175], v[136:139]
	v_mfma_f32_16x16x32_bf16 v[124:127], v[36:39], v[180:183], v[124:127]
	v_mfma_f32_16x16x32_bf16 v[120:123], v[44:47], v[180:183], v[120:123]
	v_mfma_f32_16x16x32_bf16 v[108:111], v[36:39], v[188:191], v[108:111]
	v_mfma_f32_16x16x32_bf16 v[104:107], v[44:47], v[188:191], v[104:107]
	s_setprio 0
	s_setprio 1
	v_mfma_f32_16x16x32_bf16 v[148:151], v[48:51], v[160:163], v[148:151]
	v_mfma_f32_16x16x32_bf16 v[144:147], v[64:67], v[160:163], v[144:147]
	v_mfma_f32_16x16x32_bf16 v[132:135], v[48:51], v[168:171], v[132:135]
	v_mfma_f32_16x16x32_bf16 v[128:131], v[64:67], v[168:171], v[128:131]
	v_mfma_f32_16x16x32_bf16 v[116:119], v[48:51], v[176:179], v[116:119]
	v_mfma_f32_16x16x32_bf16 v[112:115], v[64:67], v[176:179], v[112:115]
	v_mfma_f32_16x16x32_bf16 v[100:103], v[48:51], v[184:187], v[100:103]
	v_mfma_f32_16x16x32_bf16 v[96:99], v[64:67], v[184:187], v[96:99]
	v_mfma_f32_16x16x32_bf16 v[148:151], v[56:59], v[164:167], v[148:151]
	v_mfma_f32_16x16x32_bf16 v[144:147], v[68:71], v[164:167], v[144:147]
	v_mfma_f32_16x16x32_bf16 v[132:135], v[56:59], v[172:175], v[132:135]
	v_mfma_f32_16x16x32_bf16 v[128:131], v[68:71], v[172:175], v[128:131]
	v_mfma_f32_16x16x32_bf16 v[116:119], v[56:59], v[180:183], v[116:119]
	v_mfma_f32_16x16x32_bf16 v[112:115], v[68:71], v[180:183], v[112:115]
	v_mfma_f32_16x16x32_bf16 v[100:103], v[56:59], v[188:191], v[100:103]
	v_mfma_f32_16x16x32_bf16 v[96:99], v[68:71], v[188:191], v[96:99]
	s_setprio 0
	s_barrier
	s_add_i32 s69, s63, s49
	v_lshl_add_u64 v[222:223], s[12:13], 0, v[196:197]
	s_mov_b32 m0, s69
	ds_read_b128 v[160:163], v234 offset:16384
	ds_read_b128 v[164:167], v234 offset:17408
	ds_read_b128 v[168:171], v234 offset:18432
	ds_read_b128 v[172:175], v234 offset:19456
	ds_read_b128 v[176:179], v234 offset:20480
	ds_read_b128 v[180:183], v234 offset:21504
	ds_read_b128 v[184:187], v234 offset:22528
	ds_read_b128 v[188:191], v234 offset:23552
	global_load_lds_dwordx4 v[222:223], off
	s_add_i32 m0, s69, 0x2000
	s_add_u32 s70, s12, 0x40000
	v_lshl_add_u64 v[224:225], s[12:13], 0, v[200:201]
	s_addc_u32 s71, s13, 0
	s_add_i32 s69, s64, s49
	global_load_lds_dwordx4 v[224:225], off
	s_mov_b32 m0, s69
	v_lshl_add_u64 v[240:241], s[44:45], 0, v[194:195]
	global_load_lds_dwordx4 v196, s[70:71]
	s_add_i32 m0, s69, 0x2000
	v_lshl_add_u64 v[242:243], s[44:45], 0, v[198:199]
	global_load_lds_dwordx4 v200, s[70:71]
	s_mov_b32 m0, s50
	s_nop 0
	global_load_lds_dwordx4 v[240:241], off
	s_mov_b32 m0, s51
	s_nop 0
	global_load_lds_dwordx4 v[242:243], off
	s_waitcnt vmcnt(8)
	s_waitcnt lgkmcnt(0)
	s_barrier
	s_setprio 1
	s_waitcnt lgkmcnt(0)
	v_mfma_f32_16x16x32_bf16 v[92:95], v[32:35], v[160:163], v[92:95]
	v_mfma_f32_16x16x32_bf16 v[88:91], v[40:43], v[160:163], v[88:91]
	v_mfma_f32_16x16x32_bf16 v[76:79], v[32:35], v[168:171], v[76:79]
	v_mfma_f32_16x16x32_bf16 v[72:75], v[40:43], v[168:171], v[72:75]
	v_mfma_f32_16x16x32_bf16 v[28:31], v[32:35], v[176:179], v[28:31]
	v_mfma_f32_16x16x32_bf16 v[24:27], v[40:43], v[176:179], v[24:27]
	v_mfma_f32_16x16x32_bf16 v[12:15], v[32:35], v[184:187], v[12:15]
	v_mfma_f32_16x16x32_bf16 v[8:11], v[40:43], v[184:187], v[8:11]
	v_mfma_f32_16x16x32_bf16 v[92:95], v[36:39], v[164:167], v[92:95]
	v_mfma_f32_16x16x32_bf16 v[88:91], v[44:47], v[164:167], v[88:91]
	v_mfma_f32_16x16x32_bf16 v[76:79], v[36:39], v[172:175], v[76:79]
	v_mfma_f32_16x16x32_bf16 v[72:75], v[44:47], v[172:175], v[72:75]
	v_mfma_f32_16x16x32_bf16 v[28:31], v[36:39], v[180:183], v[28:31]
	v_mfma_f32_16x16x32_bf16 v[24:27], v[44:47], v[180:183], v[24:27]
	v_mfma_f32_16x16x32_bf16 v[12:15], v[36:39], v[188:191], v[12:15]
	v_mfma_f32_16x16x32_bf16 v[8:11], v[44:47], v[188:191], v[8:11]
	s_setprio 0
	s_setprio 1
	v_mfma_f32_16x16x32_bf16 v[20:23], v[48:51], v[176:179], v[20:23]
	v_mfma_f32_16x16x32_bf16 v[16:19], v[64:67], v[176:179], v[16:19]
	v_mfma_f32_16x16x32_bf16 v[4:7], v[48:51], v[184:187], v[4:7]
	v_mfma_f32_16x16x32_bf16 v[0:3], v[64:67], v[184:187], v[0:3]
	v_mfma_f32_16x16x32_bf16 v[32:35], v[48:51], v[160:163], v[84:87]
	v_mfma_f32_16x16x32_bf16 v[36:39], v[64:67], v[160:163], v[80:83]
	v_mfma_f32_16x16x32_bf16 v[40:43], v[48:51], v[168:171], v[60:63]
	v_mfma_f32_16x16x32_bf16 v[44:47], v[64:67], v[168:171], v[52:55]
	v_mfma_f32_16x16x32_bf16 v[20:23], v[56:59], v[180:183], v[20:23]
	v_mfma_f32_16x16x32_bf16 v[16:19], v[68:71], v[180:183], v[16:19]
	v_mfma_f32_16x16x32_bf16 v[4:7], v[56:59], v[188:191], v[4:7]
	v_mfma_f32_16x16x32_bf16 v[0:3], v[68:71], v[188:191], v[0:3]
	v_mfma_f32_16x16x32_bf16 v[32:35], v[56:59], v[164:167], v[32:35]
	v_mfma_f32_16x16x32_bf16 v[36:39], v[68:71], v[164:167], v[36:39]
	v_mfma_f32_16x16x32_bf16 v[40:43], v[56:59], v[172:175], v[40:43]
	v_mfma_f32_16x16x32_bf16 v[44:47], v[68:71], v[172:175], v[44:47]
	s_setprio 0
	s_barrier
	s_add_i32 s69, 0, 0x18000
	s_add_i32 s70, 0, 0x1c000
	v_add_u32_e32 v60, s69, v231
	v_add_u32_e32 v80, s70, v231
	ds_read_b128 v[48:51], v60
	ds_read_b128 v[52:55], v60 offset:1024
	ds_read_b128 v[56:59], v60 offset:2048
	ds_read_b128 v[60:63], v60 offset:3072
	ds_read_b128 v[64:67], v80
	ds_read_b128 v[68:71], v80 offset:1024
	ds_read_b128 v[160:163], v80 offset:2048
	ds_read_b128 v[164:167], v80 offset:3072
	s_add_u32 s44, s44, 0x40000
	s_addc_u32 s45, s45, 0
	s_mov_b32 m0, s54
	ds_read_b128 v[80:83], v234 offset:32768
	ds_read_b128 v[84:87], v234 offset:33792
	ds_read_b128 v[168:171], v234 offset:34816
	ds_read_b128 v[172:175], v234 offset:35840
	ds_read_b128 v[176:179], v234 offset:36864
	ds_read_b128 v[180:183], v234 offset:37888
	ds_read_b128 v[184:187], v234 offset:38912
	ds_read_b128 v[188:191], v234 offset:39936
	global_load_lds_dwordx4 v194, s[44:45]
	s_mov_b32 m0, s55
	s_nop 0
	global_load_lds_dwordx4 v198, s[44:45]
	s_waitcnt vmcnt(8)
	s_waitcnt lgkmcnt(0)
	s_barrier
	s_setprio 1
	s_waitcnt lgkmcnt(0)
	v_mfma_f32_16x16x32_bf16 v[156:159], v[48:51], v[80:83], v[156:159]
	v_mfma_f32_16x16x32_bf16 v[152:155], v[56:59], v[80:83], v[152:155]
	v_mfma_f32_16x16x32_bf16 v[140:143], v[48:51], v[168:171], v[140:143]
	v_mfma_f32_16x16x32_bf16 v[136:139], v[56:59], v[168:171], v[136:139]
	v_mfma_f32_16x16x32_bf16 v[124:127], v[48:51], v[176:179], v[124:127]
	v_mfma_f32_16x16x32_bf16 v[120:123], v[56:59], v[176:179], v[120:123]
	v_mfma_f32_16x16x32_bf16 v[108:111], v[48:51], v[184:187], v[108:111]
	v_mfma_f32_16x16x32_bf16 v[104:107], v[56:59], v[184:187], v[104:107]
	v_mfma_f32_16x16x32_bf16 v[156:159], v[52:55], v[84:87], v[156:159]
	v_mfma_f32_16x16x32_bf16 v[152:155], v[60:63], v[84:87], v[152:155]
	v_mfma_f32_16x16x32_bf16 v[140:143], v[52:55], v[172:175], v[140:143]
	v_mfma_f32_16x16x32_bf16 v[136:139], v[60:63], v[172:175], v[136:139]
	v_mfma_f32_16x16x32_bf16 v[124:127], v[52:55], v[180:183], v[124:127]
	v_mfma_f32_16x16x32_bf16 v[120:123], v[60:63], v[180:183], v[120:123]
	v_mfma_f32_16x16x32_bf16 v[108:111], v[52:55], v[188:191], v[108:111]
	v_mfma_f32_16x16x32_bf16 v[104:107], v[60:63], v[188:191], v[104:107]
	s_setprio 0
	s_setprio 1
	v_mfma_f32_16x16x32_bf16 v[148:151], v[64:67], v[80:83], v[148:151]
	v_mfma_f32_16x16x32_bf16 v[80:83], v[160:163], v[80:83], v[144:147]
	v_mfma_f32_16x16x32_bf16 v[144:147], v[164:167], v[84:87], v[80:83]
	v_mfma_f32_16x16x32_bf16 v[80:83], v[64:67], v[168:171], v[132:135]
	v_mfma_f32_16x16x32_bf16 v[132:135], v[68:71], v[172:175], v[80:83]
	v_mfma_f32_16x16x32_bf16 v[80:83], v[160:163], v[168:171], v[128:131]
	v_mfma_f32_16x16x32_bf16 v[128:131], v[164:167], v[172:175], v[80:83]
	v_mfma_f32_16x16x32_bf16 v[80:83], v[64:67], v[176:179], v[116:119]
	v_mfma_f32_16x16x32_bf16 v[116:119], v[68:71], v[180:183], v[80:83]
	v_mfma_f32_16x16x32_bf16 v[80:83], v[160:163], v[176:179], v[112:115]
	v_mfma_f32_16x16x32_bf16 v[112:115], v[164:167], v[180:183], v[80:83]
	v_mfma_f32_16x16x32_bf16 v[80:83], v[64:67], v[184:187], v[100:103]
	v_mfma_f32_16x16x32_bf16 v[100:103], v[68:71], v[188:191], v[80:83]
	v_mfma_f32_16x16x32_bf16 v[80:83], v[160:163], v[184:187], v[96:99]
	v_mfma_f32_16x16x32_bf16 v[148:151], v[68:71], v[84:87], v[148:151]
	v_mfma_f32_16x16x32_bf16 v[96:99], v[164:167], v[188:191], v[80:83]
	s_setprio 0
	s_barrier
	s_add_i32 s44, s69, s49
	v_lshl_add_u64 v[84:85], v[222:223], 0, s[24:25]
	s_mov_b32 m0, s44
	s_nop 0
	ds_read_b128 v[80:83], v234 offset:49152
	ds_read_b128 v[168:171], v234 offset:50176
	ds_read_b128 v[172:175], v234 offset:51200
	ds_read_b128 v[176:179], v234 offset:52224
	ds_read_b128 v[180:183], v234 offset:53248
	ds_read_b128 v[184:187], v234 offset:54272
	ds_read_b128 v[188:191], v234 offset:55296
	ds_read_b128 v[218:221], v234 offset:56320
	global_load_lds_dwordx4 v[84:85], off
	s_add_i32 m0, s44, 0x2000
	s_add_u32 s12, s12, 0x40080
	v_lshl_add_u64 v[84:85], v[224:225], 0, s[24:25]
	s_addc_u32 s13, s13, 0
	s_add_i32 s44, s70, s49
	global_load_lds_dwordx4 v[84:85], off
	s_mov_b32 m0, s44
	s_nop 0
	global_load_lds_dwordx4 v196, s[12:13]
	s_add_i32 m0, s44, 0x2000
	s_nop 0
	global_load_lds_dwordx4 v200, s[12:13]
	v_lshl_add_u64 v[84:85], v[240:241], 0, s[24:25]
	s_mov_b32 m0, s58
	s_nop 0
	global_load_lds_dwordx4 v[84:85], off
	v_lshl_add_u64 v[84:85], v[242:243], 0, s[24:25]
	s_mov_b32 m0, s59
	s_nop 0
	global_load_lds_dwordx4 v[84:85], off
	s_waitcnt vmcnt(8)
	s_waitcnt lgkmcnt(0)
	s_barrier
	s_setprio 1
	s_waitcnt lgkmcnt(0)
	v_mfma_f32_16x16x32_bf16 v[84:87], v[48:51], v[80:83], v[92:95]
	v_mfma_f32_16x16x32_bf16 v[92:95], v[52:55], v[168:171], v[84:87]
	v_mfma_f32_16x16x32_bf16 v[84:87], v[56:59], v[80:83], v[88:91]
	v_mfma_f32_16x16x32_bf16 v[76:79], v[48:51], v[172:175], v[76:79]
	v_mfma_f32_16x16x32_bf16 v[72:75], v[56:59], v[172:175], v[72:75]
	v_mfma_f32_16x16x32_bf16 v[28:31], v[48:51], v[180:183], v[28:31]
	v_mfma_f32_16x16x32_bf16 v[24:27], v[56:59], v[180:183], v[24:27]
	v_mfma_f32_16x16x32_bf16 v[12:15], v[48:51], v[188:191], v[12:15]
	v_mfma_f32_16x16x32_bf16 v[8:11], v[56:59], v[188:191], v[8:11]
	v_mfma_f32_16x16x32_bf16 v[88:91], v[60:63], v[168:171], v[84:87]
	v_mfma_f32_16x16x32_bf16 v[76:79], v[52:55], v[176:179], v[76:79]
	v_mfma_f32_16x16x32_bf16 v[72:75], v[60:63], v[176:179], v[72:75]
	v_mfma_f32_16x16x32_bf16 v[28:31], v[52:55], v[184:187], v[28:31]
	v_mfma_f32_16x16x32_bf16 v[24:27], v[60:63], v[184:187], v[24:27]
	v_mfma_f32_16x16x32_bf16 v[12:15], v[52:55], v[218:221], v[12:15]
	v_mfma_f32_16x16x32_bf16 v[8:11], v[60:63], v[218:221], v[8:11]
	s_setprio 0
	s_setprio 1
	v_mfma_f32_16x16x32_bf16 v[32:35], v[64:67], v[80:83], v[32:35]
	v_mfma_f32_16x16x32_bf16 v[84:87], v[68:71], v[168:171], v[32:35]
	v_mfma_f32_16x16x32_bf16 v[32:35], v[160:163], v[80:83], v[36:39]
	v_mfma_f32_16x16x32_bf16 v[80:83], v[164:167], v[168:171], v[32:35]
	v_mfma_f32_16x16x32_bf16 v[32:35], v[64:67], v[172:175], v[40:43]
	v_mfma_f32_16x16x32_bf16 v[60:63], v[68:71], v[176:179], v[32:35]
	v_mfma_f32_16x16x32_bf16 v[32:35], v[160:163], v[172:175], v[44:47]
	v_mfma_f32_16x16x32_bf16 v[20:23], v[64:67], v[180:183], v[20:23]
	v_mfma_f32_16x16x32_bf16 v[16:19], v[160:163], v[180:183], v[16:19]
	v_mfma_f32_16x16x32_bf16 v[4:7], v[64:67], v[188:191], v[4:7]
	v_mfma_f32_16x16x32_bf16 v[0:3], v[160:163], v[188:191], v[0:3]
	v_mfma_f32_16x16x32_bf16 v[52:55], v[164:167], v[176:179], v[32:35]
	v_mfma_f32_16x16x32_bf16 v[20:23], v[68:71], v[184:187], v[20:23]
	v_mfma_f32_16x16x32_bf16 v[16:19], v[164:167], v[184:187], v[16:19]
	v_mfma_f32_16x16x32_bf16 v[4:7], v[68:71], v[218:221], v[4:7]
	v_mfma_f32_16x16x32_bf16 v[0:3], v[164:167], v[218:221], v[0:3]
	s_setprio 0
	s_barrier
	s_add_i32 s68, s68, 2
	s_add_u32 s10, s10, 0x100
	s_addc_u32 s11, s11, 0
	s_add_u32 s33, s33, 0x100
	s_addc_u32 s67, s67, 0
	s_cmp_gt_u32 s68, 13
	s_cbranch_scc0 .LBB0_768
	s_and_b64 vcc, exec, s[26:27]
	s_cbranch_vccz .LBB0_771
	s_barrier

.LBB0_953:
	ds_read_b128 v[138:141], v133
	ds_read_b128 v[142:145], v133 offset:1024
	ds_read_b128 v[146:149], v133 offset:2048
	ds_read_b128 v[164:167], v133 offset:3072
	ds_read_b128 v[168:171], v134
	ds_read_b128 v[172:175], v134 offset:1024
	ds_read_b128 v[176:179], v134 offset:2048
	ds_read_b128 v[200:203], v134 offset:3072
	s_add_u32 s10, s8, 0xfffc0080
	s_addc_u32 s11, s9, -1
	s_cmp_lg_u32 s22, 12
	s_cselect_b32 s10, s10, 0
	s_cselect_b32 s11, s11, 0
	s_add_u32 s12, s4, s10
	s_addc_u32 s13, s5, s11
	s_add_u32 s10, s0, s10
	s_addc_u32 s11, s1, s11
	s_mov_b32 m0, s23
	v_lshl_add_u64 v[150:151], v[128:129], 0, s[8:9]
	ds_read_b128 v[204:207], v135
	ds_read_b128 v[208:211], v135 offset:1024
	ds_read_b128 v[212:215], v135 offset:2048
	ds_read_b128 v[216:219], v135 offset:3072
	ds_read_b128 v[220:223], v135 offset:4096
	ds_read_b128 v[228:231], v135 offset:5120
	ds_read_b128 v[232:235], v135 offset:6144
	ds_read_b128 v[236:239], v135 offset:7168
	global_load_lds_dwordx4 v[150:151], off
	v_lshl_add_u64 v[150:151], v[130:131], 0, s[8:9]
	s_mov_b32 m0, s24
	s_nop 0
	global_load_lds_dwordx4 v[150:151], off
	s_waitcnt vmcnt(8)
	s_waitcnt lgkmcnt(0)
	s_barrier
	s_setprio 1
	s_waitcnt lgkmcnt(0)
	v_mfma_f32_16x16x32_bf16 v[124:127], v[138:141], v[204:207], v[124:127]
	v_mfma_f32_16x16x32_bf16 v[120:123], v[146:149], v[204:207], v[120:123]
	v_mfma_f32_16x16x32_bf16 v[108:111], v[138:141], v[212:215], v[108:111]
	v_mfma_f32_16x16x32_bf16 v[104:107], v[146:149], v[212:215], v[104:107]
	v_mfma_f32_16x16x32_bf16 v[92:95], v[138:141], v[220:223], v[92:95]
	v_mfma_f32_16x16x32_bf16 v[88:91], v[146:149], v[220:223], v[88:91]
	v_mfma_f32_16x16x32_bf16 v[76:79], v[138:141], v[232:235], v[76:79]
	v_mfma_f32_16x16x32_bf16 v[72:75], v[146:149], v[232:235], v[72:75]
	v_mfma_f32_16x16x32_bf16 v[124:127], v[142:145], v[208:211], v[124:127]
	v_mfma_f32_16x16x32_bf16 v[120:123], v[164:167], v[208:211], v[120:123]
	v_mfma_f32_16x16x32_bf16 v[108:111], v[142:145], v[216:219], v[108:111]
	v_mfma_f32_16x16x32_bf16 v[104:107], v[164:167], v[216:219], v[104:107]
	v_mfma_f32_16x16x32_bf16 v[92:95], v[142:145], v[228:231], v[92:95]
	v_mfma_f32_16x16x32_bf16 v[88:91], v[164:167], v[228:231], v[88:91]
	v_mfma_f32_16x16x32_bf16 v[76:79], v[142:145], v[236:239], v[76:79]
	v_mfma_f32_16x16x32_bf16 v[72:75], v[164:167], v[236:239], v[72:75]
	s_setprio 0
	s_setprio 1
	v_mfma_f32_16x16x32_bf16 v[116:119], v[168:171], v[204:207], v[116:119]
	v_mfma_f32_16x16x32_bf16 v[112:115], v[176:179], v[204:207], v[112:115]
	v_mfma_f32_16x16x32_bf16 v[100:103], v[168:171], v[212:215], v[100:103]
	v_mfma_f32_16x16x32_bf16 v[96:99], v[176:179], v[212:215], v[96:99]
	v_mfma_f32_16x16x32_bf16 v[84:87], v[168:171], v[220:223], v[84:87]
	v_mfma_f32_16x16x32_bf16 v[80:83], v[176:179], v[220:223], v[80:83]
	v_mfma_f32_16x16x32_bf16 v[68:71], v[168:171], v[232:235], v[68:71]
	v_mfma_f32_16x16x32_bf16 v[64:67], v[176:179], v[232:235], v[64:67]
	v_mfma_f32_16x16x32_bf16 v[116:119], v[172:175], v[208:211], v[116:119]
	v_mfma_f32_16x16x32_bf16 v[112:115], v[200:203], v[208:211], v[112:115]
	v_mfma_f32_16x16x32_bf16 v[100:103], v[172:175], v[216:219], v[100:103]
	v_mfma_f32_16x16x32_bf16 v[96:99], v[200:203], v[216:219], v[96:99]
	v_mfma_f32_16x16x32_bf16 v[84:87], v[172:175], v[228:231], v[84:87]
	v_mfma_f32_16x16x32_bf16 v[80:83], v[200:203], v[228:231], v[80:83]
	v_mfma_f32_16x16x32_bf16 v[68:71], v[172:175], v[236:239], v[68:71]
	v_mfma_f32_16x16x32_bf16 v[64:67], v[200:203], v[236:239], v[64:67]
	s_setprio 0
	s_barrier
	s_mov_b32 m0, s25
	v_lshl_add_u64 v[150:151], s[10:11], 0, v[156:157]
	s_add_u32 s36, s10, 0x40000
	ds_read_b128 v[204:207], v135 offset:16384
	ds_read_b128 v[208:211], v135 offset:17408
	ds_read_b128 v[212:215], v135 offset:18432
	ds_read_b128 v[216:219], v135 offset:19456
	ds_read_b128 v[220:223], v135 offset:20480
	ds_read_b128 v[228:231], v135 offset:21504
	ds_read_b128 v[232:235], v135 offset:22528
	ds_read_b128 v[236:239], v135 offset:23552
	global_load_lds_dwordx4 v[150:151], off
	v_lshl_add_u64 v[180:181], s[10:11], 0, v[152:153]
	s_mov_b32 m0, s26
	s_addc_u32 s37, s11, 0
	global_load_lds_dwordx4 v[180:181], off
	s_mov_b32 m0, s27
	v_lshl_add_u64 v[240:241], s[12:13], 0, v[154:155]
	global_load_lds_dwordx4 v156, s[36:37]
	s_mov_b32 m0, s28
	s_nop 0
	global_load_lds_dwordx4 v152, s[36:37]
	v_lshl_add_u64 v[224:225], s[12:13], 0, v[158:159]
	s_mov_b32 m0, s15
	s_nop 0
	global_load_lds_dwordx4 v[224:225], off
	s_mov_b32 m0, s16
	s_nop 0
	global_load_lds_dwordx4 v[240:241], off
	s_waitcnt vmcnt(8)
	s_waitcnt lgkmcnt(0)
	s_barrier
	s_setprio 1
	s_waitcnt lgkmcnt(0)
	v_mfma_f32_16x16x32_bf16 v[60:63], v[138:141], v[204:207], v[60:63]
	v_mfma_f32_16x16x32_bf16 v[56:59], v[146:149], v[204:207], v[56:59]
	v_mfma_f32_16x16x32_bf16 v[44:47], v[138:141], v[212:215], v[44:47]
	v_mfma_f32_16x16x32_bf16 v[40:43], v[146:149], v[212:215], v[40:43]
	v_mfma_f32_16x16x32_bf16 v[28:31], v[138:141], v[220:223], v[28:31]
	v_mfma_f32_16x16x32_bf16 v[24:27], v[146:149], v[220:223], v[24:27]
	v_mfma_f32_16x16x32_bf16 v[12:15], v[138:141], v[232:235], v[12:15]
	v_mfma_f32_16x16x32_bf16 v[8:11], v[146:149], v[232:235], v[8:11]
	v_mfma_f32_16x16x32_bf16 v[60:63], v[142:145], v[208:211], v[60:63]
	v_mfma_f32_16x16x32_bf16 v[56:59], v[164:167], v[208:211], v[56:59]
	v_mfma_f32_16x16x32_bf16 v[44:47], v[142:145], v[216:219], v[44:47]
	v_mfma_f32_16x16x32_bf16 v[40:43], v[164:167], v[216:219], v[40:43]
	v_mfma_f32_16x16x32_bf16 v[28:31], v[142:145], v[228:231], v[28:31]
	v_mfma_f32_16x16x32_bf16 v[24:27], v[164:167], v[228:231], v[24:27]
	v_mfma_f32_16x16x32_bf16 v[12:15], v[142:145], v[236:239], v[12:15]
	v_mfma_f32_16x16x32_bf16 v[8:11], v[164:167], v[236:239], v[8:11]
	s_setprio 0
	s_setprio 1
	v_mfma_f32_16x16x32_bf16 v[52:55], v[168:171], v[204:207], v[52:55]
	v_mfma_f32_16x16x32_bf16 v[48:51], v[176:179], v[204:207], v[48:51]
	v_mfma_f32_16x16x32_bf16 v[36:39], v[168:171], v[212:215], v[36:39]
	v_mfma_f32_16x16x32_bf16 v[32:35], v[176:179], v[212:215], v[32:35]
	v_mfma_f32_16x16x32_bf16 v[20:23], v[168:171], v[220:223], v[20:23]
	v_mfma_f32_16x16x32_bf16 v[16:19], v[176:179], v[220:223], v[16:19]
	v_mfma_f32_16x16x32_bf16 v[4:7], v[168:171], v[232:235], v[4:7]
	v_mfma_f32_16x16x32_bf16 v[0:3], v[176:179], v[232:235], v[0:3]
	v_mfma_f32_16x16x32_bf16 v[52:55], v[172:175], v[208:211], v[52:55]
	v_mfma_f32_16x16x32_bf16 v[48:51], v[200:203], v[208:211], v[48:51]
	v_mfma_f32_16x16x32_bf16 v[36:39], v[172:175], v[216:219], v[36:39]
	v_mfma_f32_16x16x32_bf16 v[32:35], v[200:203], v[216:219], v[32:35]
	v_mfma_f32_16x16x32_bf16 v[20:23], v[172:175], v[228:231], v[20:23]
	v_mfma_f32_16x16x32_bf16 v[16:19], v[200:203], v[228:231], v[16:19]
	v_mfma_f32_16x16x32_bf16 v[4:7], v[172:175], v[236:239], v[4:7]
	v_mfma_f32_16x16x32_bf16 v[0:3], v[200:203], v[236:239], v[0:3]
	s_setprio 0
	s_barrier
	ds_read_b128 v[138:141], v136
	ds_read_b128 v[142:145], v136 offset:1024
	ds_read_b128 v[146:149], v136 offset:2048
	ds_read_b128 v[164:167], v136 offset:3072
	ds_read_b128 v[168:171], v137
	ds_read_b128 v[172:175], v137 offset:1024
	ds_read_b128 v[176:179], v137 offset:2048
	ds_read_b128 v[200:203], v137 offset:3072
	s_add_u32 s12, s12, 0x40000
	s_addc_u32 s13, s13, 0
	s_mov_b32 m0, s17
	ds_read_b128 v[204:207], v135 offset:32768
	ds_read_b128 v[208:211], v135 offset:33792
	ds_read_b128 v[212:215], v135 offset:34816
	ds_read_b128 v[216:219], v135 offset:35840
	ds_read_b128 v[220:223], v135 offset:36864
	ds_read_b128 v[228:231], v135 offset:37888
	ds_read_b128 v[232:235], v135 offset:38912
	ds_read_b128 v[236:239], v135 offset:39936
	global_load_lds_dwordx4 v158, s[12:13]
	s_mov_b32 m0, s18
	s_nop 0
	global_load_lds_dwordx4 v154, s[12:13]
	s_waitcnt vmcnt(8)
	s_waitcnt lgkmcnt(0)
	s_barrier
	s_setprio 1
	s_waitcnt lgkmcnt(0)
	v_mfma_f32_16x16x32_bf16 v[124:127], v[138:141], v[204:207], v[124:127]
	v_mfma_f32_16x16x32_bf16 v[120:123], v[146:149], v[204:207], v[120:123]
	v_mfma_f32_16x16x32_bf16 v[108:111], v[138:141], v[212:215], v[108:111]
	v_mfma_f32_16x16x32_bf16 v[104:107], v[146:149], v[212:215], v[104:107]
	v_mfma_f32_16x16x32_bf16 v[92:95], v[138:141], v[220:223], v[92:95]
	v_mfma_f32_16x16x32_bf16 v[88:91], v[146:149], v[220:223], v[88:91]
	v_mfma_f32_16x16x32_bf16 v[76:79], v[138:141], v[232:235], v[76:79]
	v_mfma_f32_16x16x32_bf16 v[72:75], v[146:149], v[232:235], v[72:75]
	v_mfma_f32_16x16x32_bf16 v[124:127], v[142:145], v[208:211], v[124:127]
	v_mfma_f32_16x16x32_bf16 v[120:123], v[164:167], v[208:211], v[120:123]
	v_mfma_f32_16x16x32_bf16 v[108:111], v[142:145], v[216:219], v[108:111]
	v_mfma_f32_16x16x32_bf16 v[104:107], v[164:167], v[216:219], v[104:107]
	v_mfma_f32_16x16x32_bf16 v[92:95], v[142:145], v[228:231], v[92:95]
	v_mfma_f32_16x16x32_bf16 v[88:91], v[164:167], v[228:231], v[88:91]
	v_mfma_f32_16x16x32_bf16 v[76:79], v[142:145], v[236:239], v[76:79]
	v_mfma_f32_16x16x32_bf16 v[72:75], v[164:167], v[236:239], v[72:75]
	s_setprio 0
	s_setprio 1
	v_mfma_f32_16x16x32_bf16 v[116:119], v[168:171], v[204:207], v[116:119]
	v_mfma_f32_16x16x32_bf16 v[112:115], v[176:179], v[204:207], v[112:115]
	v_mfma_f32_16x16x32_bf16 v[100:103], v[168:171], v[212:215], v[100:103]
	v_mfma_f32_16x16x32_bf16 v[96:99], v[176:179], v[212:215], v[96:99]
	v_mfma_f32_16x16x32_bf16 v[84:87], v[168:171], v[220:223], v[84:87]
	v_mfma_f32_16x16x32_bf16 v[80:83], v[176:179], v[220:223], v[80:83]
	v_mfma_f32_16x16x32_bf16 v[68:71], v[168:171], v[232:235], v[68:71]
	v_mfma_f32_16x16x32_bf16 v[64:67], v[176:179], v[232:235], v[64:67]
	v_mfma_f32_16x16x32_bf16 v[116:119], v[172:175], v[208:211], v[116:119]
	v_mfma_f32_16x16x32_bf16 v[112:115], v[200:203], v[208:211], v[112:115]
	v_mfma_f32_16x16x32_bf16 v[100:103], v[172:175], v[216:219], v[100:103]
	v_mfma_f32_16x16x32_bf16 v[96:99], v[200:203], v[216:219], v[96:99]
	v_mfma_f32_16x16x32_bf16 v[84:87], v[172:175], v[228:231], v[84:87]
	v_mfma_f32_16x16x32_bf16 v[80:83], v[200:203], v[228:231], v[80:83]
	v_mfma_f32_16x16x32_bf16 v[68:71], v[172:175], v[236:239], v[68:71]
	v_mfma_f32_16x16x32_bf16 v[64:67], v[200:203], v[236:239], v[64:67]
	s_setprio 0
	s_barrier
	s_mov_b32 m0, s29
	v_lshl_add_u64 v[150:151], v[150:151], 0, s[6:7]
	s_add_u32 s10, s10, 0x40080
	ds_read_b128 v[204:207], v135 offset:49152
	ds_read_b128 v[208:211], v135 offset:50176
	ds_read_b128 v[212:215], v135 offset:51200
	ds_read_b128 v[216:219], v135 offset:52224
	ds_read_b128 v[220:223], v135 offset:53248
	ds_read_b128 v[228:231], v135 offset:54272
	ds_read_b128 v[232:235], v135 offset:55296
	ds_read_b128 v[236:239], v135 offset:56320
	global_load_lds_dwordx4 v[150:151], off
	v_lshl_add_u64 v[150:151], v[180:181], 0, s[6:7]
	s_mov_b32 m0, s30
	s_addc_u32 s11, s11, 0
	global_load_lds_dwordx4 v[150:151], off
	s_mov_b32 m0, s31
	s_nop 0
	global_load_lds_dwordx4 v156, s[10:11]
	s_mov_b32 m0, s34
	s_nop 0
	global_load_lds_dwordx4 v152, s[10:11]
	v_lshl_add_u64 v[150:151], v[224:225], 0, s[6:7]
	s_mov_b32 m0, s20
	s_nop 0
	global_load_lds_dwordx4 v[150:151], off
	v_lshl_add_u64 v[150:151], v[240:241], 0, s[6:7]
	s_mov_b32 m0, s21
	s_nop 0
	global_load_lds_dwordx4 v[150:151], off
	s_waitcnt vmcnt(8)
	s_waitcnt lgkmcnt(0)
	s_barrier
	s_setprio 1
	s_waitcnt lgkmcnt(0)
	v_mfma_f32_16x16x32_bf16 v[60:63], v[138:141], v[204:207], v[60:63]
	v_mfma_f32_16x16x32_bf16 v[56:59], v[146:149], v[204:207], v[56:59]
	v_mfma_f32_16x16x32_bf16 v[44:47], v[138:141], v[212:215], v[44:47]
	v_mfma_f32_16x16x32_bf16 v[40:43], v[146:149], v[212:215], v[40:43]
	v_mfma_f32_16x16x32_bf16 v[28:31], v[138:141], v[220:223], v[28:31]
	v_mfma_f32_16x16x32_bf16 v[24:27], v[146:149], v[220:223], v[24:27]
	v_mfma_f32_16x16x32_bf16 v[12:15], v[138:141], v[232:235], v[12:15]
	v_mfma_f32_16x16x32_bf16 v[8:11], v[146:149], v[232:235], v[8:11]
	v_mfma_f32_16x16x32_bf16 v[60:63], v[142:145], v[208:211], v[60:63]
	v_mfma_f32_16x16x32_bf16 v[56:59], v[164:167], v[208:211], v[56:59]
	v_mfma_f32_16x16x32_bf16 v[44:47], v[142:145], v[216:219], v[44:47]
	v_mfma_f32_16x16x32_bf16 v[40:43], v[164:167], v[216:219], v[40:43]
	v_mfma_f32_16x16x32_bf16 v[28:31], v[142:145], v[228:231], v[28:31]
	v_mfma_f32_16x16x32_bf16 v[24:27], v[164:167], v[228:231], v[24:27]
	v_mfma_f32_16x16x32_bf16 v[12:15], v[142:145], v[236:239], v[12:15]
	v_mfma_f32_16x16x32_bf16 v[8:11], v[164:167], v[236:239], v[8:11]
	s_setprio 0
	s_setprio 1
	v_mfma_f32_16x16x32_bf16 v[52:55], v[168:171], v[204:207], v[52:55]
	v_mfma_f32_16x16x32_bf16 v[48:51], v[176:179], v[204:207], v[48:51]
	v_mfma_f32_16x16x32_bf16 v[36:39], v[168:171], v[212:215], v[36:39]
	v_mfma_f32_16x16x32_bf16 v[32:35], v[176:179], v[212:215], v[32:35]
	v_mfma_f32_16x16x32_bf16 v[20:23], v[168:171], v[220:223], v[20:23]
	v_mfma_f32_16x16x32_bf16 v[16:19], v[176:179], v[220:223], v[16:19]
	v_mfma_f32_16x16x32_bf16 v[4:7], v[168:171], v[232:235], v[4:7]
	v_mfma_f32_16x16x32_bf16 v[0:3], v[176:179], v[232:235], v[0:3]
	v_mfma_f32_16x16x32_bf16 v[52:55], v[172:175], v[208:211], v[52:55]
	v_mfma_f32_16x16x32_bf16 v[48:51], v[200:203], v[208:211], v[48:51]
	v_mfma_f32_16x16x32_bf16 v[36:39], v[172:175], v[216:219], v[36:39]
	v_mfma_f32_16x16x32_bf16 v[32:35], v[200:203], v[216:219], v[32:35]
	v_mfma_f32_16x16x32_bf16 v[20:23], v[172:175], v[228:231], v[20:23]
	v_mfma_f32_16x16x32_bf16 v[16:19], v[200:203], v[228:231], v[16:19]
	v_mfma_f32_16x16x32_bf16 v[4:7], v[172:175], v[236:239], v[4:7]
	v_mfma_f32_16x16x32_bf16 v[0:3], v[200:203], v[236:239], v[0:3]
	s_setprio 0
	s_barrier
	s_add_i32 s22, s22, 2
	s_add_u32 s8, s8, 0x100
	s_addc_u32 s9, s9, 0
	s_cmp_gt_u32 s22, 13
	s_cbranch_scc0 .LBB0_953
	s_cmpk_lt_u32 s14, 0x100
	s_cbranch_scc0 .LBB0_956
	s_barrier

.LBB0_994:
	ds_read_b128 v[128:131], v144
	ds_read_b128 v[132:135], v144 offset:1024
	ds_read_b128 v[164:167], v144 offset:2048
	ds_read_b128 v[168:171], v144 offset:3072
	ds_read_b128 v[172:175], v145
	ds_read_b128 v[176:179], v145 offset:1024
	ds_read_b128 v[194:197], v145 offset:2048
	ds_read_b128 v[198:201], v145 offset:3072
	s_add_u32 s4, s0, 0xfffc0080
	s_addc_u32 s5, s1, -1
	s_cmp_eq_u32 s76, 12
	s_cselect_b32 s47, s43, s5
	s_cselect_b32 s46, s72, s4
	s_cselect_b32 s5, s37, s75
	s_cselect_b32 s4, s73, s74
	s_add_i32 m0, s58, 0xc000
	ds_read_b128 v[202:205], v146
	ds_read_b128 v[206:209], v146 offset:1024
	ds_read_b128 v[210:213], v146 offset:2048
	ds_read_b128 v[214:217], v146 offset:3072
	ds_read_b128 v[218:221], v146 offset:4096
	ds_read_b128 v[222:225], v146 offset:5120
	ds_read_b128 v[228:231], v146 offset:6144
	ds_read_b128 v[232:235], v146 offset:7168
	global_load_lds_dwordx4 v160, s[0:1]
	s_add_i32 m0, s58, 0xe000
	s_nop 0
	global_load_lds_dwordx4 v162, s[0:1]
	s_waitcnt vmcnt(8)
	s_waitcnt lgkmcnt(0)
	s_barrier
	s_setprio 1
	s_waitcnt lgkmcnt(0)
	v_mfma_f32_16x16x32_bf16 v[124:127], v[128:131], v[202:205], v[124:127]
	v_mfma_f32_16x16x32_bf16 v[120:123], v[164:167], v[202:205], v[120:123]
	v_mfma_f32_16x16x32_bf16 v[108:111], v[128:131], v[210:213], v[108:111]
	v_mfma_f32_16x16x32_bf16 v[104:107], v[164:167], v[210:213], v[104:107]
	v_mfma_f32_16x16x32_bf16 v[92:95], v[128:131], v[218:221], v[92:95]
	v_mfma_f32_16x16x32_bf16 v[88:91], v[164:167], v[218:221], v[88:91]
	v_mfma_f32_16x16x32_bf16 v[76:79], v[128:131], v[228:231], v[76:79]
	v_mfma_f32_16x16x32_bf16 v[72:75], v[164:167], v[228:231], v[72:75]
	v_mfma_f32_16x16x32_bf16 v[124:127], v[132:135], v[206:209], v[124:127]
	v_mfma_f32_16x16x32_bf16 v[120:123], v[168:171], v[206:209], v[120:123]
	v_mfma_f32_16x16x32_bf16 v[108:111], v[132:135], v[214:217], v[108:111]
	v_mfma_f32_16x16x32_bf16 v[104:107], v[168:171], v[214:217], v[104:107]
	v_mfma_f32_16x16x32_bf16 v[92:95], v[132:135], v[222:225], v[92:95]
	v_mfma_f32_16x16x32_bf16 v[88:91], v[168:171], v[222:225], v[88:91]
	v_mfma_f32_16x16x32_bf16 v[76:79], v[132:135], v[232:235], v[76:79]
	v_mfma_f32_16x16x32_bf16 v[72:75], v[168:171], v[232:235], v[72:75]
	s_setprio 0
	s_setprio 1
	v_mfma_f32_16x16x32_bf16 v[116:119], v[172:175], v[202:205], v[116:119]
	v_mfma_f32_16x16x32_bf16 v[112:115], v[194:197], v[202:205], v[112:115]
	v_mfma_f32_16x16x32_bf16 v[100:103], v[172:175], v[210:213], v[100:103]
	v_mfma_f32_16x16x32_bf16 v[96:99], v[194:197], v[210:213], v[96:99]
	v_mfma_f32_16x16x32_bf16 v[84:87], v[172:175], v[218:221], v[84:87]
	v_mfma_f32_16x16x32_bf16 v[80:83], v[194:197], v[218:221], v[80:83]
	v_mfma_f32_16x16x32_bf16 v[68:71], v[172:175], v[228:231], v[68:71]
	v_mfma_f32_16x16x32_bf16 v[64:67], v[194:197], v[228:231], v[64:67]
	v_mfma_f32_16x16x32_bf16 v[116:119], v[176:179], v[206:209], v[116:119]
	v_mfma_f32_16x16x32_bf16 v[112:115], v[198:201], v[206:209], v[112:115]
	v_mfma_f32_16x16x32_bf16 v[100:103], v[176:179], v[214:217], v[100:103]
	v_mfma_f32_16x16x32_bf16 v[96:99], v[198:201], v[214:217], v[96:99]
	v_mfma_f32_16x16x32_bf16 v[84:87], v[176:179], v[222:225], v[84:87]
	v_mfma_f32_16x16x32_bf16 v[80:83], v[198:201], v[222:225], v[80:83]
	v_mfma_f32_16x16x32_bf16 v[68:71], v[176:179], v[232:235], v[68:71]
	v_mfma_f32_16x16x32_bf16 v[64:67], v[198:201], v[232:235], v[64:67]
	s_setprio 0
	s_barrier
	s_add_i32 s77, s48, s57
	v_lshl_add_u64 v[136:137], s[4:5], 0, v[156:157]
	s_mov_b32 m0, s77
	ds_read_b128 v[202:205], v146 offset:16384
	ds_read_b128 v[206:209], v146 offset:17408
	ds_read_b128 v[210:213], v146 offset:18432
	ds_read_b128 v[214:217], v146 offset:19456
	ds_read_b128 v[218:221], v146 offset:20480
	ds_read_b128 v[222:225], v146 offset:21504
	ds_read_b128 v[228:231], v146 offset:22528
	ds_read_b128 v[232:235], v146 offset:23552
	global_load_lds_dwordx4 v[136:137], off
	s_add_i32 m0, s77, 0x2000
	s_add_u32 s78, s4, 0x40000
	v_lshl_add_u64 v[150:151], s[4:5], 0, v[152:153]
	s_addc_u32 s79, s5, 0
	s_add_i32 s77, s49, s57
	global_load_lds_dwordx4 v[150:151], off
	s_mov_b32 m0, s77
	v_lshl_add_u64 v[236:237], s[46:47], 0, v[154:155]
	global_load_lds_dwordx4 v156, s[78:79]
	s_add_i32 m0, s77, 0x2000
	s_nop 0
	global_load_lds_dwordx4 v152, s[78:79]
	v_lshl_add_u64 v[180:181], s[46:47], 0, v[158:159]
	s_mov_b32 m0, s58
	s_nop 0
	global_load_lds_dwordx4 v[180:181], off
	s_mov_b32 m0, s59
	s_nop 0
	global_load_lds_dwordx4 v[236:237], off
	s_waitcnt vmcnt(8)
	s_waitcnt lgkmcnt(0)
	s_barrier
	s_setprio 1
	s_waitcnt lgkmcnt(0)
	v_mfma_f32_16x16x32_bf16 v[60:63], v[128:131], v[202:205], v[60:63]
	v_mfma_f32_16x16x32_bf16 v[56:59], v[164:167], v[202:205], v[56:59]
	v_mfma_f32_16x16x32_bf16 v[44:47], v[128:131], v[210:213], v[44:47]
	v_mfma_f32_16x16x32_bf16 v[40:43], v[164:167], v[210:213], v[40:43]
	v_mfma_f32_16x16x32_bf16 v[28:31], v[128:131], v[218:221], v[28:31]
	v_mfma_f32_16x16x32_bf16 v[24:27], v[164:167], v[218:221], v[24:27]
	v_mfma_f32_16x16x32_bf16 v[12:15], v[128:131], v[228:231], v[12:15]
	v_mfma_f32_16x16x32_bf16 v[8:11], v[164:167], v[228:231], v[8:11]
	v_mfma_f32_16x16x32_bf16 v[60:63], v[132:135], v[206:209], v[60:63]
	v_mfma_f32_16x16x32_bf16 v[56:59], v[168:171], v[206:209], v[56:59]
	v_mfma_f32_16x16x32_bf16 v[44:47], v[132:135], v[214:217], v[44:47]
	v_mfma_f32_16x16x32_bf16 v[40:43], v[168:171], v[214:217], v[40:43]
	v_mfma_f32_16x16x32_bf16 v[28:31], v[132:135], v[222:225], v[28:31]
	v_mfma_f32_16x16x32_bf16 v[24:27], v[168:171], v[222:225], v[24:27]
	v_mfma_f32_16x16x32_bf16 v[12:15], v[132:135], v[232:235], v[12:15]
	v_mfma_f32_16x16x32_bf16 v[8:11], v[168:171], v[232:235], v[8:11]
	s_setprio 0
	s_setprio 1
	v_mfma_f32_16x16x32_bf16 v[52:55], v[172:175], v[202:205], v[52:55]
	v_mfma_f32_16x16x32_bf16 v[48:51], v[194:197], v[202:205], v[48:51]
	v_mfma_f32_16x16x32_bf16 v[36:39], v[172:175], v[210:213], v[36:39]
	v_mfma_f32_16x16x32_bf16 v[32:35], v[194:197], v[210:213], v[32:35]
	v_mfma_f32_16x16x32_bf16 v[20:23], v[172:175], v[218:221], v[20:23]
	v_mfma_f32_16x16x32_bf16 v[16:19], v[194:197], v[218:221], v[16:19]
	v_mfma_f32_16x16x32_bf16 v[4:7], v[172:175], v[228:231], v[4:7]
	v_mfma_f32_16x16x32_bf16 v[0:3], v[194:197], v[228:231], v[0:3]
	v_mfma_f32_16x16x32_bf16 v[52:55], v[176:179], v[206:209], v[52:55]
	v_mfma_f32_16x16x32_bf16 v[48:51], v[198:201], v[206:209], v[48:51]
	v_mfma_f32_16x16x32_bf16 v[36:39], v[176:179], v[214:217], v[36:39]
	v_mfma_f32_16x16x32_bf16 v[32:35], v[198:201], v[214:217], v[32:35]
	v_mfma_f32_16x16x32_bf16 v[20:23], v[176:179], v[222:225], v[20:23]
	v_mfma_f32_16x16x32_bf16 v[16:19], v[198:201], v[222:225], v[16:19]
	v_mfma_f32_16x16x32_bf16 v[4:7], v[176:179], v[232:235], v[4:7]
	v_mfma_f32_16x16x32_bf16 v[0:3], v[198:201], v[232:235], v[0:3]
	s_setprio 0
	s_barrier
	v_add_u32_e32 v149, s51, v142
	ds_read_b128 v[128:131], v149
	ds_read_b128 v[132:135], v149 offset:1024
	ds_read_b128 v[164:167], v149 offset:2048
	ds_read_b128 v[168:171], v149 offset:3072
	v_add_u32_e32 v149, s53, v142
	ds_read_b128 v[172:175], v149
	ds_read_b128 v[176:179], v149 offset:1024
	ds_read_b128 v[194:197], v149 offset:2048
	ds_read_b128 v[198:201], v149 offset:3072
	s_add_u32 s46, s46, 0x40000
	s_addc_u32 s47, s47, 0
	s_mov_b32 m0, s60
	ds_read_b128 v[202:205], v146 offset:32768
	ds_read_b128 v[206:209], v146 offset:33792
	ds_read_b128 v[210:213], v146 offset:34816
	ds_read_b128 v[214:217], v146 offset:35840
	ds_read_b128 v[218:221], v146 offset:36864
	ds_read_b128 v[222:225], v146 offset:37888
	ds_read_b128 v[228:231], v146 offset:38912
	ds_read_b128 v[232:235], v146 offset:39936
	global_load_lds_dwordx4 v158, s[46:47]
	s_mov_b32 m0, s61
	s_nop 0
	global_load_lds_dwordx4 v154, s[46:47]
	s_waitcnt vmcnt(8)
	s_waitcnt lgkmcnt(0)
	s_barrier
	s_setprio 1
	s_waitcnt lgkmcnt(0)
	v_mfma_f32_16x16x32_bf16 v[124:127], v[128:131], v[202:205], v[124:127]
	v_mfma_f32_16x16x32_bf16 v[120:123], v[164:167], v[202:205], v[120:123]
	v_mfma_f32_16x16x32_bf16 v[108:111], v[128:131], v[210:213], v[108:111]
	v_mfma_f32_16x16x32_bf16 v[104:107], v[164:167], v[210:213], v[104:107]
	v_mfma_f32_16x16x32_bf16 v[92:95], v[128:131], v[218:221], v[92:95]
	v_mfma_f32_16x16x32_bf16 v[88:91], v[164:167], v[218:221], v[88:91]
	v_mfma_f32_16x16x32_bf16 v[76:79], v[128:131], v[228:231], v[76:79]
	v_mfma_f32_16x16x32_bf16 v[72:75], v[164:167], v[228:231], v[72:75]
	v_mfma_f32_16x16x32_bf16 v[124:127], v[132:135], v[206:209], v[124:127]
	v_mfma_f32_16x16x32_bf16 v[120:123], v[168:171], v[206:209], v[120:123]
	v_mfma_f32_16x16x32_bf16 v[108:111], v[132:135], v[214:217], v[108:111]
	v_mfma_f32_16x16x32_bf16 v[104:107], v[168:171], v[214:217], v[104:107]
	v_mfma_f32_16x16x32_bf16 v[92:95], v[132:135], v[222:225], v[92:95]
	v_mfma_f32_16x16x32_bf16 v[88:91], v[168:171], v[222:225], v[88:91]
	v_mfma_f32_16x16x32_bf16 v[76:79], v[132:135], v[232:235], v[76:79]
	v_mfma_f32_16x16x32_bf16 v[72:75], v[168:171], v[232:235], v[72:75]
	s_setprio 0
	s_setprio 1
	v_mfma_f32_16x16x32_bf16 v[116:119], v[172:175], v[202:205], v[116:119]
	v_mfma_f32_16x16x32_bf16 v[112:115], v[194:197], v[202:205], v[112:115]
	v_mfma_f32_16x16x32_bf16 v[100:103], v[172:175], v[210:213], v[100:103]
	v_mfma_f32_16x16x32_bf16 v[96:99], v[194:197], v[210:213], v[96:99]
	v_mfma_f32_16x16x32_bf16 v[84:87], v[172:175], v[218:221], v[84:87]
	v_mfma_f32_16x16x32_bf16 v[80:83], v[194:197], v[218:221], v[80:83]
	v_mfma_f32_16x16x32_bf16 v[68:71], v[172:175], v[228:231], v[68:71]
	v_mfma_f32_16x16x32_bf16 v[64:67], v[194:197], v[228:231], v[64:67]
	v_mfma_f32_16x16x32_bf16 v[116:119], v[176:179], v[206:209], v[116:119]
	v_mfma_f32_16x16x32_bf16 v[112:115], v[198:201], v[206:209], v[112:115]
	v_mfma_f32_16x16x32_bf16 v[100:103], v[176:179], v[214:217], v[100:103]
	v_mfma_f32_16x16x32_bf16 v[96:99], v[198:201], v[214:217], v[96:99]
	v_mfma_f32_16x16x32_bf16 v[84:87], v[176:179], v[222:225], v[84:87]
	v_mfma_f32_16x16x32_bf16 v[80:83], v[198:201], v[222:225], v[80:83]
	v_mfma_f32_16x16x32_bf16 v[68:71], v[176:179], v[232:235], v[68:71]
	v_mfma_f32_16x16x32_bf16 v[64:67], v[198:201], v[232:235], v[64:67]
	s_setprio 0
	s_barrier
	s_add_i32 s46, s51, s57
	v_lshl_add_u64 v[136:137], v[136:137], 0, s[22:23]
	s_mov_b32 m0, s46
	ds_read_b128 v[202:205], v146 offset:49152
	ds_read_b128 v[206:209], v146 offset:50176
	ds_read_b128 v[210:213], v146 offset:51200
	ds_read_b128 v[214:217], v146 offset:52224
	ds_read_b128 v[218:221], v146 offset:53248
	ds_read_b128 v[222:225], v146 offset:54272
	ds_read_b128 v[228:231], v146 offset:55296
	ds_read_b128 v[232:235], v146 offset:56320
	global_load_lds_dwordx4 v[136:137], off
	s_add_i32 m0, s46, 0x2000
	s_add_u32 s4, s4, 0x40080
	v_lshl_add_u64 v[136:137], v[150:151], 0, s[22:23]
	s_addc_u32 s5, s5, 0
	s_add_i32 s46, s53, s57
	global_load_lds_dwordx4 v[136:137], off
	s_mov_b32 m0, s46
	s_nop 0
	global_load_lds_dwordx4 v156, s[4:5]
	s_add_i32 m0, s46, 0x2000
	s_nop 0
	global_load_lds_dwordx4 v152, s[4:5]
	v_lshl_add_u64 v[136:137], v[180:181], 0, s[22:23]
	s_mov_b32 m0, s62
	s_nop 0
	global_load_lds_dwordx4 v[136:137], off
	v_lshl_add_u64 v[136:137], v[236:237], 0, s[22:23]
	s_mov_b32 m0, s63
	s_nop 0
	global_load_lds_dwordx4 v[136:137], off
	s_waitcnt vmcnt(8)
	s_waitcnt lgkmcnt(0)
	s_barrier
	s_setprio 1
	s_waitcnt lgkmcnt(0)
	v_mfma_f32_16x16x32_bf16 v[60:63], v[128:131], v[202:205], v[60:63]
	v_mfma_f32_16x16x32_bf16 v[56:59], v[164:167], v[202:205], v[56:59]
	v_mfma_f32_16x16x32_bf16 v[44:47], v[128:131], v[210:213], v[44:47]
	v_mfma_f32_16x16x32_bf16 v[40:43], v[164:167], v[210:213], v[40:43]
	v_mfma_f32_16x16x32_bf16 v[28:31], v[128:131], v[218:221], v[28:31]
	v_mfma_f32_16x16x32_bf16 v[24:27], v[164:167], v[218:221], v[24:27]
	v_mfma_f32_16x16x32_bf16 v[12:15], v[128:131], v[228:231], v[12:15]
	v_mfma_f32_16x16x32_bf16 v[8:11], v[164:167], v[228:231], v[8:11]
	v_mfma_f32_16x16x32_bf16 v[60:63], v[132:135], v[206:209], v[60:63]
	v_mfma_f32_16x16x32_bf16 v[56:59], v[168:171], v[206:209], v[56:59]
	v_mfma_f32_16x16x32_bf16 v[44:47], v[132:135], v[214:217], v[44:47]
	v_mfma_f32_16x16x32_bf16 v[40:43], v[168:171], v[214:217], v[40:43]
	v_mfma_f32_16x16x32_bf16 v[28:31], v[132:135], v[222:225], v[28:31]
	v_mfma_f32_16x16x32_bf16 v[24:27], v[168:171], v[222:225], v[24:27]
	v_mfma_f32_16x16x32_bf16 v[12:15], v[132:135], v[232:235], v[12:15]
	v_mfma_f32_16x16x32_bf16 v[8:11], v[168:171], v[232:235], v[8:11]
	s_setprio 0
	s_setprio 1
	v_mfma_f32_16x16x32_bf16 v[52:55], v[172:175], v[202:205], v[52:55]
	v_mfma_f32_16x16x32_bf16 v[48:51], v[194:197], v[202:205], v[48:51]
	v_mfma_f32_16x16x32_bf16 v[36:39], v[172:175], v[210:213], v[36:39]
	v_mfma_f32_16x16x32_bf16 v[32:35], v[194:197], v[210:213], v[32:35]
	v_mfma_f32_16x16x32_bf16 v[20:23], v[172:175], v[218:221], v[20:23]
	v_mfma_f32_16x16x32_bf16 v[16:19], v[194:197], v[218:221], v[16:19]
	v_mfma_f32_16x16x32_bf16 v[4:7], v[172:175], v[228:231], v[4:7]
	v_mfma_f32_16x16x32_bf16 v[0:3], v[194:197], v[228:231], v[0:3]
	v_mfma_f32_16x16x32_bf16 v[52:55], v[176:179], v[206:209], v[52:55]
	v_mfma_f32_16x16x32_bf16 v[48:51], v[198:201], v[206:209], v[48:51]
	v_mfma_f32_16x16x32_bf16 v[36:39], v[176:179], v[214:217], v[36:39]
	v_mfma_f32_16x16x32_bf16 v[32:35], v[198:201], v[214:217], v[32:35]
	v_mfma_f32_16x16x32_bf16 v[20:23], v[176:179], v[222:225], v[20:23]
	v_mfma_f32_16x16x32_bf16 v[16:19], v[198:201], v[222:225], v[16:19]
	v_mfma_f32_16x16x32_bf16 v[4:7], v[176:179], v[232:235], v[4:7]
	v_mfma_f32_16x16x32_bf16 v[0:3], v[198:201], v[232:235], v[0:3]
	s_setprio 0
	s_barrier
	s_add_i32 s76, s76, 2
	s_add_u32 s0, s0, 0x100
	s_addc_u32 s1, s1, 0
	s_add_u32 s74, s74, 0x100
	s_addc_u32 s75, s75, 0
	s_cmp_gt_u32 s76, 13
	s_cbranch_scc0 .LBB0_994
	s_and_b64 vcc, exec, s[24:25]
	s_cbranch_vccz .LBB0_997
	s_barrier

.LBB0_1017:
	ds_read_b128 v[146:149], v140
	ds_read_b128 v[150:153], v140 offset:1024
	ds_read_b128 v[154:157], v140 offset:2048
	ds_read_b128 v[158:161], v140 offset:3072
	ds_read_b128 v[162:165], v142
	ds_read_b128 v[166:169], v142 offset:1024
	ds_read_b128 v[170:173], v142 offset:2048
	ds_read_b128 v[174:177], v142 offset:3072
	s_add_u32 s12, s10, 0xfff00080
	s_addc_u32 s13, s11, -1
	s_cmp_eq_u32 s26, 60
	s_cselect_b32 s15, s3, s13
	s_cselect_b32 s14, s2, s12
	s_cselect_b32 s13, s1, s25
	s_cselect_b32 s12, s0, s24
	s_mov_b32 m0, s27
	ds_read_b128 v[178:181], v143
	ds_read_b128 v[184:187], v143 offset:1024
	ds_read_b128 v[188:191], v143 offset:2048
	ds_read_b128 v[192:195], v143 offset:3072
	ds_read_b128 v[196:199], v143 offset:4096
	ds_read_b128 v[200:203], v143 offset:5120
	ds_read_b128 v[204:207], v143 offset:6144
	ds_read_b128 v[208:211], v143 offset:7168
	global_load_lds_dwordx4 v136, s[10:11]
	s_mov_b32 m0, s28
	s_nop 0
	global_load_lds_dwordx4 v138, s[10:11]
	s_waitcnt vmcnt(8)
	s_waitcnt lgkmcnt(0)
	s_barrier
	s_setprio 1
	s_waitcnt lgkmcnt(0)
	v_mfma_f32_16x16x32_bf16 v[124:127], v[146:149], v[178:181], v[124:127]
	v_mfma_f32_16x16x32_bf16 v[120:123], v[154:157], v[178:181], v[120:123]
	v_mfma_f32_16x16x32_bf16 v[112:115], v[146:149], v[188:191], v[112:115]
	v_mfma_f32_16x16x32_bf16 v[104:107], v[154:157], v[188:191], v[104:107]
	v_mfma_f32_16x16x32_bf16 v[96:99], v[146:149], v[196:199], v[96:99]
	v_mfma_f32_16x16x32_bf16 v[88:91], v[154:157], v[196:199], v[88:91]
	v_mfma_f32_16x16x32_bf16 v[80:83], v[146:149], v[204:207], v[80:83]
	v_mfma_f32_16x16x32_bf16 v[72:75], v[154:157], v[204:207], v[72:75]
	v_mfma_f32_16x16x32_bf16 v[124:127], v[150:153], v[184:187], v[124:127]
	v_mfma_f32_16x16x32_bf16 v[120:123], v[158:161], v[184:187], v[120:123]
	v_mfma_f32_16x16x32_bf16 v[112:115], v[150:153], v[192:195], v[112:115]
	v_mfma_f32_16x16x32_bf16 v[104:107], v[158:161], v[192:195], v[104:107]
	v_mfma_f32_16x16x32_bf16 v[96:99], v[150:153], v[200:203], v[96:99]
	v_mfma_f32_16x16x32_bf16 v[88:91], v[158:161], v[200:203], v[88:91]
	v_mfma_f32_16x16x32_bf16 v[80:83], v[150:153], v[208:211], v[80:83]
	v_mfma_f32_16x16x32_bf16 v[72:75], v[158:161], v[208:211], v[72:75]
	s_setprio 0
	s_setprio 1
	v_mfma_f32_16x16x32_bf16 v[116:119], v[162:165], v[178:181], v[116:119]
	v_mfma_f32_16x16x32_bf16 v[108:111], v[170:173], v[178:181], v[108:111]
	v_mfma_f32_16x16x32_bf16 v[100:103], v[162:165], v[188:191], v[100:103]
	v_mfma_f32_16x16x32_bf16 v[92:95], v[170:173], v[188:191], v[92:95]
	v_mfma_f32_16x16x32_bf16 v[84:87], v[162:165], v[196:199], v[84:87]
	v_mfma_f32_16x16x32_bf16 v[76:79], v[170:173], v[196:199], v[76:79]
	v_mfma_f32_16x16x32_bf16 v[68:71], v[162:165], v[204:207], v[68:71]
	v_mfma_f32_16x16x32_bf16 v[64:67], v[170:173], v[204:207], v[64:67]
	v_mfma_f32_16x16x32_bf16 v[116:119], v[166:169], v[184:187], v[116:119]
	v_mfma_f32_16x16x32_bf16 v[108:111], v[174:177], v[184:187], v[108:111]
	v_mfma_f32_16x16x32_bf16 v[100:103], v[166:169], v[192:195], v[100:103]
	v_mfma_f32_16x16x32_bf16 v[92:95], v[174:177], v[192:195], v[92:95]
	v_mfma_f32_16x16x32_bf16 v[84:87], v[166:169], v[200:203], v[84:87]
	v_mfma_f32_16x16x32_bf16 v[76:79], v[174:177], v[200:203], v[76:79]
	v_mfma_f32_16x16x32_bf16 v[68:71], v[166:169], v[208:211], v[68:71]
	v_mfma_f32_16x16x32_bf16 v[64:67], v[174:177], v[208:211], v[64:67]
	s_setprio 0
	s_barrier
	s_mov_b32 m0, s29
	v_lshl_add_u64 v[212:213], s[12:13], 0, v[132:133]
	s_add_u32 s40, s12, 0x100000
	ds_read_b128 v[178:181], v143 offset:16384
	ds_read_b128 v[184:187], v143 offset:17408
	ds_read_b128 v[188:191], v143 offset:18432
	ds_read_b128 v[192:195], v143 offset:19456
	ds_read_b128 v[196:199], v143 offset:20480
	ds_read_b128 v[200:203], v143 offset:21504
	ds_read_b128 v[204:207], v143 offset:22528
	ds_read_b128 v[208:211], v143 offset:23552
	global_load_lds_dwordx4 v[212:213], off
	v_lshl_add_u64 v[214:215], s[12:13], 0, v[128:129]
	s_mov_b32 m0, s30
	s_addc_u32 s41, s13, 0
	global_load_lds_dwordx4 v[214:215], off
	s_mov_b32 m0, s31
	v_lshl_add_u64 v[218:219], s[14:15], 0, v[130:131]
	global_load_lds_dwordx4 v132, s[40:41]
	s_mov_b32 m0, s34
	s_nop 0
	global_load_lds_dwordx4 v128, s[40:41]
	v_lshl_add_u64 v[216:217], s[14:15], 0, v[134:135]
	s_mov_b32 m0, s17
	s_nop 0
	global_load_lds_dwordx4 v[216:217], off
	s_mov_b32 m0, s18
	s_nop 0
	global_load_lds_dwordx4 v[218:219], off
	s_waitcnt vmcnt(8)
	s_waitcnt lgkmcnt(0)
	s_barrier
	s_setprio 1
	s_waitcnt lgkmcnt(0)
	v_mfma_f32_16x16x32_bf16 v[60:63], v[146:149], v[178:181], v[60:63]
	v_mfma_f32_16x16x32_bf16 v[56:59], v[154:157], v[178:181], v[56:59]
	v_mfma_f32_16x16x32_bf16 v[48:51], v[146:149], v[188:191], v[48:51]
	v_mfma_f32_16x16x32_bf16 v[40:43], v[154:157], v[188:191], v[40:43]
	v_mfma_f32_16x16x32_bf16 v[32:35], v[146:149], v[196:199], v[32:35]
	v_mfma_f32_16x16x32_bf16 v[24:27], v[154:157], v[196:199], v[24:27]
	v_mfma_f32_16x16x32_bf16 v[16:19], v[146:149], v[204:207], v[16:19]
	v_mfma_f32_16x16x32_bf16 v[8:11], v[154:157], v[204:207], v[8:11]
	v_mfma_f32_16x16x32_bf16 v[60:63], v[150:153], v[184:187], v[60:63]
	v_mfma_f32_16x16x32_bf16 v[56:59], v[158:161], v[184:187], v[56:59]
	v_mfma_f32_16x16x32_bf16 v[48:51], v[150:153], v[192:195], v[48:51]
	v_mfma_f32_16x16x32_bf16 v[40:43], v[158:161], v[192:195], v[40:43]
	v_mfma_f32_16x16x32_bf16 v[32:35], v[150:153], v[200:203], v[32:35]
	v_mfma_f32_16x16x32_bf16 v[24:27], v[158:161], v[200:203], v[24:27]
	v_mfma_f32_16x16x32_bf16 v[16:19], v[150:153], v[208:211], v[16:19]
	v_mfma_f32_16x16x32_bf16 v[8:11], v[158:161], v[208:211], v[8:11]
	s_setprio 0
	s_setprio 1
	v_mfma_f32_16x16x32_bf16 v[52:55], v[162:165], v[178:181], v[52:55]
	v_mfma_f32_16x16x32_bf16 v[44:47], v[170:173], v[178:181], v[44:47]
	v_mfma_f32_16x16x32_bf16 v[36:39], v[162:165], v[188:191], v[36:39]
	v_mfma_f32_16x16x32_bf16 v[28:31], v[170:173], v[188:191], v[28:31]
	v_mfma_f32_16x16x32_bf16 v[20:23], v[162:165], v[196:199], v[20:23]
	v_mfma_f32_16x16x32_bf16 v[12:15], v[170:173], v[196:199], v[12:15]
	v_mfma_f32_16x16x32_bf16 v[4:7], v[162:165], v[204:207], v[4:7]
	v_mfma_f32_16x16x32_bf16 v[0:3], v[170:173], v[204:207], v[0:3]
	v_mfma_f32_16x16x32_bf16 v[52:55], v[166:169], v[184:187], v[52:55]
	v_mfma_f32_16x16x32_bf16 v[44:47], v[174:177], v[184:187], v[44:47]
	v_mfma_f32_16x16x32_bf16 v[36:39], v[166:169], v[192:195], v[36:39]
	v_mfma_f32_16x16x32_bf16 v[28:31], v[174:177], v[192:195], v[28:31]
	v_mfma_f32_16x16x32_bf16 v[20:23], v[166:169], v[200:203], v[20:23]
	v_mfma_f32_16x16x32_bf16 v[12:15], v[174:177], v[200:203], v[12:15]
	v_mfma_f32_16x16x32_bf16 v[4:7], v[166:169], v[208:211], v[4:7]
	v_mfma_f32_16x16x32_bf16 v[0:3], v[174:177], v[208:211], v[0:3]
	s_setprio 0
	s_barrier
	ds_read_b128 v[146:149], v144
	ds_read_b128 v[150:153], v144 offset:1024
	ds_read_b128 v[154:157], v144 offset:2048
	ds_read_b128 v[158:161], v144 offset:3072
	ds_read_b128 v[162:165], v145
	ds_read_b128 v[166:169], v145 offset:1024
	ds_read_b128 v[170:173], v145 offset:2048
	ds_read_b128 v[174:177], v145 offset:3072
	s_add_u32 s14, s14, 0x100000
	s_addc_u32 s15, s15, 0
	s_mov_b32 m0, s19
	ds_read_b128 v[178:181], v143 offset:32768
	ds_read_b128 v[184:187], v143 offset:33792
	ds_read_b128 v[188:191], v143 offset:34816
	ds_read_b128 v[192:195], v143 offset:35840
	ds_read_b128 v[196:199], v143 offset:36864
	ds_read_b128 v[200:203], v143 offset:37888
	ds_read_b128 v[204:207], v143 offset:38912
	ds_read_b128 v[208:211], v143 offset:39936
	global_load_lds_dwordx4 v134, s[14:15]
	s_mov_b32 m0, s20
	s_nop 0
	global_load_lds_dwordx4 v130, s[14:15]
	s_waitcnt vmcnt(8)
	s_waitcnt lgkmcnt(0)
	s_barrier
	s_setprio 1
	s_waitcnt lgkmcnt(0)
	v_mfma_f32_16x16x32_bf16 v[124:127], v[146:149], v[178:181], v[124:127]
	v_mfma_f32_16x16x32_bf16 v[120:123], v[154:157], v[178:181], v[120:123]
	v_mfma_f32_16x16x32_bf16 v[112:115], v[146:149], v[188:191], v[112:115]
	v_mfma_f32_16x16x32_bf16 v[104:107], v[154:157], v[188:191], v[104:107]
	v_mfma_f32_16x16x32_bf16 v[96:99], v[146:149], v[196:199], v[96:99]
	v_mfma_f32_16x16x32_bf16 v[88:91], v[154:157], v[196:199], v[88:91]
	v_mfma_f32_16x16x32_bf16 v[80:83], v[146:149], v[204:207], v[80:83]
	v_mfma_f32_16x16x32_bf16 v[72:75], v[154:157], v[204:207], v[72:75]
	v_mfma_f32_16x16x32_bf16 v[124:127], v[150:153], v[184:187], v[124:127]
	v_mfma_f32_16x16x32_bf16 v[120:123], v[158:161], v[184:187], v[120:123]
	v_mfma_f32_16x16x32_bf16 v[112:115], v[150:153], v[192:195], v[112:115]
	v_mfma_f32_16x16x32_bf16 v[104:107], v[158:161], v[192:195], v[104:107]
	v_mfma_f32_16x16x32_bf16 v[96:99], v[150:153], v[200:203], v[96:99]
	v_mfma_f32_16x16x32_bf16 v[88:91], v[158:161], v[200:203], v[88:91]
	v_mfma_f32_16x16x32_bf16 v[80:83], v[150:153], v[208:211], v[80:83]
	v_mfma_f32_16x16x32_bf16 v[72:75], v[158:161], v[208:211], v[72:75]
	s_setprio 0
	s_setprio 1
	v_mfma_f32_16x16x32_bf16 v[116:119], v[162:165], v[178:181], v[116:119]
	v_mfma_f32_16x16x32_bf16 v[108:111], v[170:173], v[178:181], v[108:111]
	v_mfma_f32_16x16x32_bf16 v[100:103], v[162:165], v[188:191], v[100:103]
	v_mfma_f32_16x16x32_bf16 v[92:95], v[170:173], v[188:191], v[92:95]
	v_mfma_f32_16x16x32_bf16 v[84:87], v[162:165], v[196:199], v[84:87]
	v_mfma_f32_16x16x32_bf16 v[76:79], v[170:173], v[196:199], v[76:79]
	v_mfma_f32_16x16x32_bf16 v[68:71], v[162:165], v[204:207], v[68:71]
	v_mfma_f32_16x16x32_bf16 v[64:67], v[170:173], v[204:207], v[64:67]
	v_mfma_f32_16x16x32_bf16 v[116:119], v[166:169], v[184:187], v[116:119]
	v_mfma_f32_16x16x32_bf16 v[108:111], v[174:177], v[184:187], v[108:111]
	v_mfma_f32_16x16x32_bf16 v[100:103], v[166:169], v[192:195], v[100:103]
	v_mfma_f32_16x16x32_bf16 v[92:95], v[174:177], v[192:195], v[92:95]
	v_mfma_f32_16x16x32_bf16 v[84:87], v[166:169], v[200:203], v[84:87]
	v_mfma_f32_16x16x32_bf16 v[76:79], v[174:177], v[200:203], v[76:79]
	v_mfma_f32_16x16x32_bf16 v[68:71], v[166:169], v[208:211], v[68:71]
	v_mfma_f32_16x16x32_bf16 v[64:67], v[174:177], v[208:211], v[64:67]
	s_setprio 0
	s_barrier
	s_mov_b32 m0, s35
	v_lshl_add_u64 v[212:213], v[212:213], 0, s[4:5]
	s_add_u32 s12, s12, 0x100080
	ds_read_b128 v[178:181], v143 offset:49152
	ds_read_b128 v[184:187], v143 offset:50176
	ds_read_b128 v[188:191], v143 offset:51200
	ds_read_b128 v[192:195], v143 offset:52224
	ds_read_b128 v[196:199], v143 offset:53248
	ds_read_b128 v[200:203], v143 offset:54272
	ds_read_b128 v[204:207], v143 offset:55296
	ds_read_b128 v[208:211], v143 offset:56320
	global_load_lds_dwordx4 v[212:213], off
	v_lshl_add_u64 v[212:213], v[214:215], 0, s[4:5]
	s_mov_b32 m0, s36
	s_addc_u32 s13, s13, 0
	global_load_lds_dwordx4 v[212:213], off
	s_mov_b32 m0, s37
	s_nop 0
	global_load_lds_dwordx4 v132, s[12:13]
	s_mov_b32 m0, s38
	s_nop 0
	global_load_lds_dwordx4 v128, s[12:13]
	v_lshl_add_u64 v[212:213], v[216:217], 0, s[4:5]
	s_mov_b32 m0, s22
	s_nop 0
	global_load_lds_dwordx4 v[212:213], off
	v_lshl_add_u64 v[212:213], v[218:219], 0, s[4:5]
	s_mov_b32 m0, s23
	s_nop 0
	global_load_lds_dwordx4 v[212:213], off
	s_waitcnt vmcnt(8)
	s_waitcnt lgkmcnt(0)
	s_barrier
	s_setprio 1
	s_waitcnt lgkmcnt(0)
	v_mfma_f32_16x16x32_bf16 v[60:63], v[146:149], v[178:181], v[60:63]
	v_mfma_f32_16x16x32_bf16 v[56:59], v[154:157], v[178:181], v[56:59]
	v_mfma_f32_16x16x32_bf16 v[48:51], v[146:149], v[188:191], v[48:51]
	v_mfma_f32_16x16x32_bf16 v[40:43], v[154:157], v[188:191], v[40:43]
	v_mfma_f32_16x16x32_bf16 v[32:35], v[146:149], v[196:199], v[32:35]
	v_mfma_f32_16x16x32_bf16 v[24:27], v[154:157], v[196:199], v[24:27]
	v_mfma_f32_16x16x32_bf16 v[16:19], v[146:149], v[204:207], v[16:19]
	v_mfma_f32_16x16x32_bf16 v[8:11], v[154:157], v[204:207], v[8:11]
	v_mfma_f32_16x16x32_bf16 v[60:63], v[150:153], v[184:187], v[60:63]
	v_mfma_f32_16x16x32_bf16 v[56:59], v[158:161], v[184:187], v[56:59]
	v_mfma_f32_16x16x32_bf16 v[48:51], v[150:153], v[192:195], v[48:51]
	v_mfma_f32_16x16x32_bf16 v[40:43], v[158:161], v[192:195], v[40:43]
	v_mfma_f32_16x16x32_bf16 v[32:35], v[150:153], v[200:203], v[32:35]
	v_mfma_f32_16x16x32_bf16 v[24:27], v[158:161], v[200:203], v[24:27]
	v_mfma_f32_16x16x32_bf16 v[16:19], v[150:153], v[208:211], v[16:19]
	v_mfma_f32_16x16x32_bf16 v[8:11], v[158:161], v[208:211], v[8:11]
	s_setprio 0
	s_setprio 1
	v_mfma_f32_16x16x32_bf16 v[52:55], v[162:165], v[178:181], v[52:55]
	v_mfma_f32_16x16x32_bf16 v[44:47], v[170:173], v[178:181], v[44:47]
	v_mfma_f32_16x16x32_bf16 v[36:39], v[162:165], v[188:191], v[36:39]
	v_mfma_f32_16x16x32_bf16 v[28:31], v[170:173], v[188:191], v[28:31]
	v_mfma_f32_16x16x32_bf16 v[20:23], v[162:165], v[196:199], v[20:23]
	v_mfma_f32_16x16x32_bf16 v[12:15], v[170:173], v[196:199], v[12:15]
	v_mfma_f32_16x16x32_bf16 v[4:7], v[162:165], v[204:207], v[4:7]
	v_mfma_f32_16x16x32_bf16 v[0:3], v[170:173], v[204:207], v[0:3]
	v_mfma_f32_16x16x32_bf16 v[52:55], v[166:169], v[184:187], v[52:55]
	v_mfma_f32_16x16x32_bf16 v[44:47], v[174:177], v[184:187], v[44:47]
	v_mfma_f32_16x16x32_bf16 v[36:39], v[166:169], v[192:195], v[36:39]
	v_mfma_f32_16x16x32_bf16 v[28:31], v[174:177], v[192:195], v[28:31]
	v_mfma_f32_16x16x32_bf16 v[20:23], v[166:169], v[200:203], v[20:23]
	v_mfma_f32_16x16x32_bf16 v[12:15], v[174:177], v[200:203], v[12:15]
	v_mfma_f32_16x16x32_bf16 v[4:7], v[166:169], v[208:211], v[4:7]
	v_mfma_f32_16x16x32_bf16 v[0:3], v[174:177], v[208:211], v[0:3]
	s_setprio 0
	s_barrier
	s_add_i32 s26, s26, 2
	s_add_u32 s10, s10, 0x100
	s_addc_u32 s11, s11, 0
	s_add_u32 s24, s24, 0x100
	s_addc_u32 s25, s25, 0
	s_cmp_gt_u32 s26, 61
	s_cbranch_scc0 .LBB0_1017
	s_cmpk_lt_u32 s16, 0x100
	s_cbranch_scc0 .LBB0_1020
	s_barrier
